# log-forget scans hand-written: coalesced loads (lane = position mod 64), per-chunk DPP wave scan + serial carry, coalesced stores
# speedup vs baseline: 1.0086x; 1.0086x over previous
; DI void scan_unit(const Params& p, int su) {
;     const int lane = threadIdx.x & 63, wave = threadIdx.x >> 6;
;     const int seq = su * NW + wave;
;     const int e0 = lane * 65;
;     float vals[65];
;     if (seq < 32) {
;         const int b = seq >> 3, h = seq & 7;
;         const float* src = p.out + O_PBL + (size_t)b * LP * 8 + h;
;         float* dst = p.c2p + (size_t)seq * LPAD;
; #pragma unroll
;         for (int i = 0; i < 65; ++i) { const int e = e0 + i; vals[i] = src[(size_t)(e < LP ? e : LP - 1) * 8]; }
;         float s = 0.f;
; #pragma unroll
;         for (int i = 0; i < 65; ++i) s += (e0 + i < LP) ? vals[i] : 0.f;
;         float incl = s;
; #pragma unroll
;         for (int o = 1; o < 64; o <<= 1) { const float t = __shfl_up(incl, o); if (lane >= o) incl += t; }
; __global__ void __launch_bounds__(512, 2) hymba_mega(Params p) {
;     ...
;         const int su = (int)gridDim.x - 1 - (int)blockIdx.x;
;         if (su < 20) scan_unit(p, su);
.LBB0_115:
	s_or_b64 exec, exec, s[4:5]
	s_waitcnt lgkmcnt(0)
	s_barrier
	s_load_dword s33, s[0:1], 0xc8
	s_add_u32 s44, s0, 0xc8
	s_addc_u32 s45, s1, 0
	s_not_b32 s0, s2
	v_lshrrev_b32_e32 v166, 6, v138
	s_waitcnt lgkmcnt(0)
	s_add_i32 s0, s33, s0
	s_cmp_gt_i32 s0, 63
	s_cbranch_scc1 .LBB0_127
	v_and_b32_e32 v10, 63, v138
	v_lshl_add_u32 v6, v166, 6, s0
	s_nop 1
	v_readfirstlane_b32 s1, v6
	s_nop 0
	s_cmpk_gt_u32 s1, 0x9f
	s_cbranch_scc1 .LBB0_127
	s_cmp_lt_u32 s1, 32
	s_cbranch_scc0 .Lscn_smp
	s_lshr_b32 s4, s1, 3
	s_and_b32 s5, s1, 7
	s_mul_i32 s4, s4, 0x20200
	s_lshl_b32 s5, s5, 2
	s_add_i32 s4, s4, s5
	s_add_i32 s4, s4, 0xc280000
	s_add_u32 s4, s54, s4
	s_addc_u32 s5, s55, 0
	s_mul_i32 s6, s1, 0x4100
	s_add_u32 s6, s72, s6
	s_addc_u32 s7, s73, 0
	v_lshlrev_b32_e32 v11, 5, v10
	v_and_b32_e32 v12, 15, v10
	v_lshlrev_b32_e32 v12, 5, v12
	v_lshlrev_b32_e32 v13, 2, v10
	global_load_dword v20, v11, s[4:5]
	global_load_dword v21, v11, s[4:5] offset:2048
	s_add_u32 s4, s4, 0x1000
	s_addc_u32 s5, s5, 0
	global_load_dword v22, v11, s[4:5]
	global_load_dword v23, v11, s[4:5] offset:2048
	s_add_u32 s4, s4, 0x1000
	s_addc_u32 s5, s5, 0
	global_load_dword v24, v11, s[4:5]
	global_load_dword v25, v11, s[4:5] offset:2048
	s_add_u32 s4, s4, 0x1000
	s_addc_u32 s5, s5, 0
	global_load_dword v26, v11, s[4:5]
	global_load_dword v27, v11, s[4:5] offset:2048
	s_add_u32 s4, s4, 0x1000
	s_addc_u32 s5, s5, 0
	global_load_dword v28, v11, s[4:5]
	global_load_dword v29, v11, s[4:5] offset:2048
	s_add_u32 s4, s4, 0x1000
	s_addc_u32 s5, s5, 0
	global_load_dword v30, v11, s[4:5]
	global_load_dword v31, v11, s[4:5] offset:2048
	s_add_u32 s4, s4, 0x1000
	s_addc_u32 s5, s5, 0
	global_load_dword v32, v11, s[4:5]
	global_load_dword v33, v11, s[4:5] offset:2048
	s_add_u32 s4, s4, 0x1000
	s_addc_u32 s5, s5, 0
	global_load_dword v34, v11, s[4:5]
	global_load_dword v35, v11, s[4:5] offset:2048
	s_add_u32 s4, s4, 0x1000
	s_addc_u32 s5, s5, 0
	global_load_dword v36, v11, s[4:5]
	global_load_dword v37, v11, s[4:5] offset:2048
	s_add_u32 s4, s4, 0x1000
	s_addc_u32 s5, s5, 0
	global_load_dword v38, v11, s[4:5]
	global_load_dword v39, v11, s[4:5] offset:2048
	s_add_u32 s4, s4, 0x1000
	s_addc_u32 s5, s5, 0
	global_load_dword v40, v11, s[4:5]
	global_load_dword v41, v11, s[4:5] offset:2048
	s_add_u32 s4, s4, 0x1000
	s_addc_u32 s5, s5, 0
	global_load_dword v42, v11, s[4:5]
	global_load_dword v43, v11, s[4:5] offset:2048
	s_add_u32 s4, s4, 0x1000
	s_addc_u32 s5, s5, 0
	global_load_dword v44, v11, s[4:5]
	global_load_dword v45, v11, s[4:5] offset:2048
	s_add_u32 s4, s4, 0x1000
	s_addc_u32 s5, s5, 0
	global_load_dword v46, v11, s[4:5]
	global_load_dword v47, v11, s[4:5] offset:2048
	s_add_u32 s4, s4, 0x1000
	s_addc_u32 s5, s5, 0
	global_load_dword v48, v11, s[4:5]
	global_load_dword v49, v11, s[4:5] offset:2048
	s_add_u32 s4, s4, 0x1000
	s_addc_u32 s5, s5, 0
	global_load_dword v50, v11, s[4:5]
	global_load_dword v51, v11, s[4:5] offset:2048
	s_add_u32 s4, s4, 0x1000
	s_addc_u32 s5, s5, 0
	global_load_dword v52, v11, s[4:5]
	global_load_dword v53, v11, s[4:5] offset:2048
	s_add_u32 s4, s4, 0x1000
	s_addc_u32 s5, s5, 0
	global_load_dword v54, v11, s[4:5]
	global_load_dword v55, v11, s[4:5] offset:2048
	s_add_u32 s4, s4, 0x1000
	s_addc_u32 s5, s5, 0
	global_load_dword v56, v11, s[4:5]
	global_load_dword v57, v11, s[4:5] offset:2048
	s_add_u32 s4, s4, 0x1000
	s_addc_u32 s5, s5, 0
	global_load_dword v58, v11, s[4:5]
	global_load_dword v59, v11, s[4:5] offset:2048
	s_add_u32 s4, s4, 0x1000
	s_addc_u32 s5, s5, 0
	global_load_dword v60, v11, s[4:5]
	global_load_dword v61, v11, s[4:5] offset:2048
	s_add_u32 s4, s4, 0x1000
	s_addc_u32 s5, s5, 0
	global_load_dword v62, v11, s[4:5]
	global_load_dword v63, v11, s[4:5] offset:2048
	s_add_u32 s4, s4, 0x1000
	s_addc_u32 s5, s5, 0
	global_load_dword v64, v11, s[4:5]
	global_load_dword v65, v11, s[4:5] offset:2048
	s_add_u32 s4, s4, 0x1000
	s_addc_u32 s5, s5, 0
	global_load_dword v66, v11, s[4:5]
	global_load_dword v67, v11, s[4:5] offset:2048
	s_add_u32 s4, s4, 0x1000
	s_addc_u32 s5, s5, 0
	global_load_dword v68, v11, s[4:5]
	global_load_dword v69, v11, s[4:5] offset:2048
	s_add_u32 s4, s4, 0x1000
	s_addc_u32 s5, s5, 0
	global_load_dword v70, v11, s[4:5]
	global_load_dword v71, v11, s[4:5] offset:2048
	s_add_u32 s4, s4, 0x1000
	s_addc_u32 s5, s5, 0
	global_load_dword v72, v11, s[4:5]
	global_load_dword v73, v11, s[4:5] offset:2048
	s_add_u32 s4, s4, 0x1000
	s_addc_u32 s5, s5, 0
	global_load_dword v74, v11, s[4:5]
	global_load_dword v75, v11, s[4:5] offset:2048
	s_add_u32 s4, s4, 0x1000
	s_addc_u32 s5, s5, 0
	global_load_dword v76, v11, s[4:5]
	global_load_dword v77, v11, s[4:5] offset:2048
	s_add_u32 s4, s4, 0x1000
	s_addc_u32 s5, s5, 0
	global_load_dword v78, v11, s[4:5]
	global_load_dword v79, v11, s[4:5] offset:2048
	s_add_u32 s4, s4, 0x1000
	s_addc_u32 s5, s5, 0
	global_load_dword v80, v11, s[4:5]
	global_load_dword v81, v11, s[4:5] offset:2048
	s_add_u32 s4, s4, 0x1000
	s_addc_u32 s5, s5, 0
	global_load_dword v82, v11, s[4:5]
	global_load_dword v83, v11, s[4:5] offset:2048
	s_add_u32 s4, s4, 0x1000
	s_addc_u32 s5, s5, 0
	global_load_dword v84, v12, s[4:5]
	v_cmp_gt_u32_e64 s[4:5], 16, v10
	s_waitcnt vmcnt(0)
; DI void scan_unit(const Params& p, int su) {
;     ...
;         for (int i = 0; i < 65; ++i) { const int e = e0 + i; vals[i] = src[(size_t)(e < LP ? e : LP - 1) * 8]; }
;         float s = 0.f;
; #pragma unroll
;         for (int i = 0; i < 65; ++i) s += (e0 + i < LP) ? vals[i] : 0.f;
;         float incl = s;
; #pragma unroll
;         for (int o = 1; o < 64; o <<= 1) { const float t = __shfl_up(incl, o); if (lane >= o) incl += t; }
	v_cndmask_b32_e64 v84, 0, v84, s[4:5]
	v_add_f32_dpp v20, v20, v20 row_shr:1 row_mask:0xf bank_mask:0xf
	v_add_f32_dpp v21, v21, v21 row_shr:1 row_mask:0xf bank_mask:0xf
	v_add_f32_dpp v22, v22, v22 row_shr:1 row_mask:0xf bank_mask:0xf
	v_add_f32_dpp v23, v23, v23 row_shr:1 row_mask:0xf bank_mask:0xf
	v_add_f32_dpp v20, v20, v20 row_shr:2 row_mask:0xf bank_mask:0xf
	v_add_f32_dpp v21, v21, v21 row_shr:2 row_mask:0xf bank_mask:0xf
	v_add_f32_dpp v22, v22, v22 row_shr:2 row_mask:0xf bank_mask:0xf
	v_add_f32_dpp v23, v23, v23 row_shr:2 row_mask:0xf bank_mask:0xf
	v_add_f32_dpp v20, v20, v20 row_shr:4 row_mask:0xf bank_mask:0xf
	v_add_f32_dpp v21, v21, v21 row_shr:4 row_mask:0xf bank_mask:0xf
	v_add_f32_dpp v22, v22, v22 row_shr:4 row_mask:0xf bank_mask:0xf
	v_add_f32_dpp v23, v23, v23 row_shr:4 row_mask:0xf bank_mask:0xf
	v_add_f32_dpp v20, v20, v20 row_shr:8 row_mask:0xf bank_mask:0xf
	v_add_f32_dpp v21, v21, v21 row_shr:8 row_mask:0xf bank_mask:0xf
	v_add_f32_dpp v22, v22, v22 row_shr:8 row_mask:0xf bank_mask:0xf
	v_add_f32_dpp v23, v23, v23 row_shr:8 row_mask:0xf bank_mask:0xf
	v_add_f32_dpp v20, v20, v20 row_bcast:15 row_mask:0xa bank_mask:0xf
	v_add_f32_dpp v21, v21, v21 row_bcast:15 row_mask:0xa bank_mask:0xf
	v_add_f32_dpp v22, v22, v22 row_bcast:15 row_mask:0xa bank_mask:0xf
	v_add_f32_dpp v23, v23, v23 row_bcast:15 row_mask:0xa bank_mask:0xf
	v_add_f32_dpp v20, v20, v20 row_bcast:31 row_mask:0xc bank_mask:0xf
	v_add_f32_dpp v21, v21, v21 row_bcast:31 row_mask:0xc bank_mask:0xf
	v_add_f32_dpp v22, v22, v22 row_bcast:31 row_mask:0xc bank_mask:0xf
	v_add_f32_dpp v23, v23, v23 row_bcast:31 row_mask:0xc bank_mask:0xf
	v_add_f32_dpp v24, v24, v24 row_shr:1 row_mask:0xf bank_mask:0xf
	v_add_f32_dpp v25, v25, v25 row_shr:1 row_mask:0xf bank_mask:0xf
	v_add_f32_dpp v26, v26, v26 row_shr:1 row_mask:0xf bank_mask:0xf
	v_add_f32_dpp v27, v27, v27 row_shr:1 row_mask:0xf bank_mask:0xf
	v_add_f32_dpp v24, v24, v24 row_shr:2 row_mask:0xf bank_mask:0xf
	v_add_f32_dpp v25, v25, v25 row_shr:2 row_mask:0xf bank_mask:0xf
	v_add_f32_dpp v26, v26, v26 row_shr:2 row_mask:0xf bank_mask:0xf
	v_add_f32_dpp v27, v27, v27 row_shr:2 row_mask:0xf bank_mask:0xf
	v_add_f32_dpp v24, v24, v24 row_shr:4 row_mask:0xf bank_mask:0xf
	v_add_f32_dpp v25, v25, v25 row_shr:4 row_mask:0xf bank_mask:0xf
	v_add_f32_dpp v26, v26, v26 row_shr:4 row_mask:0xf bank_mask:0xf
	v_add_f32_dpp v27, v27, v27 row_shr:4 row_mask:0xf bank_mask:0xf
	v_add_f32_dpp v24, v24, v24 row_shr:8 row_mask:0xf bank_mask:0xf
	v_add_f32_dpp v25, v25, v25 row_shr:8 row_mask:0xf bank_mask:0xf
	v_add_f32_dpp v26, v26, v26 row_shr:8 row_mask:0xf bank_mask:0xf
	v_add_f32_dpp v27, v27, v27 row_shr:8 row_mask:0xf bank_mask:0xf
	v_add_f32_dpp v24, v24, v24 row_bcast:15 row_mask:0xa bank_mask:0xf
	v_add_f32_dpp v25, v25, v25 row_bcast:15 row_mask:0xa bank_mask:0xf
	v_add_f32_dpp v26, v26, v26 row_bcast:15 row_mask:0xa bank_mask:0xf
	v_add_f32_dpp v27, v27, v27 row_bcast:15 row_mask:0xa bank_mask:0xf
	v_add_f32_dpp v24, v24, v24 row_bcast:31 row_mask:0xc bank_mask:0xf
	v_add_f32_dpp v25, v25, v25 row_bcast:31 row_mask:0xc bank_mask:0xf
	v_add_f32_dpp v26, v26, v26 row_bcast:31 row_mask:0xc bank_mask:0xf
	v_add_f32_dpp v27, v27, v27 row_bcast:31 row_mask:0xc bank_mask:0xf
	v_add_f32_dpp v28, v28, v28 row_shr:1 row_mask:0xf bank_mask:0xf
	v_add_f32_dpp v29, v29, v29 row_shr:1 row_mask:0xf bank_mask:0xf
	v_add_f32_dpp v30, v30, v30 row_shr:1 row_mask:0xf bank_mask:0xf
	v_add_f32_dpp v31, v31, v31 row_shr:1 row_mask:0xf bank_mask:0xf
	v_add_f32_dpp v28, v28, v28 row_shr:2 row_mask:0xf bank_mask:0xf
	v_add_f32_dpp v29, v29, v29 row_shr:2 row_mask:0xf bank_mask:0xf
	v_add_f32_dpp v30, v30, v30 row_shr:2 row_mask:0xf bank_mask:0xf
	v_add_f32_dpp v31, v31, v31 row_shr:2 row_mask:0xf bank_mask:0xf
	v_add_f32_dpp v28, v28, v28 row_shr:4 row_mask:0xf bank_mask:0xf
	v_add_f32_dpp v29, v29, v29 row_shr:4 row_mask:0xf bank_mask:0xf
	v_add_f32_dpp v30, v30, v30 row_shr:4 row_mask:0xf bank_mask:0xf
	v_add_f32_dpp v31, v31, v31 row_shr:4 row_mask:0xf bank_mask:0xf
	v_add_f32_dpp v28, v28, v28 row_shr:8 row_mask:0xf bank_mask:0xf
	v_add_f32_dpp v29, v29, v29 row_shr:8 row_mask:0xf bank_mask:0xf
	v_add_f32_dpp v30, v30, v30 row_shr:8 row_mask:0xf bank_mask:0xf
	v_add_f32_dpp v31, v31, v31 row_shr:8 row_mask:0xf bank_mask:0xf
	v_add_f32_dpp v28, v28, v28 row_bcast:15 row_mask:0xa bank_mask:0xf
	v_add_f32_dpp v29, v29, v29 row_bcast:15 row_mask:0xa bank_mask:0xf
	v_add_f32_dpp v30, v30, v30 row_bcast:15 row_mask:0xa bank_mask:0xf
	v_add_f32_dpp v31, v31, v31 row_bcast:15 row_mask:0xa bank_mask:0xf
	v_add_f32_dpp v28, v28, v28 row_bcast:31 row_mask:0xc bank_mask:0xf
	v_add_f32_dpp v29, v29, v29 row_bcast:31 row_mask:0xc bank_mask:0xf
	v_add_f32_dpp v30, v30, v30 row_bcast:31 row_mask:0xc bank_mask:0xf
	v_add_f32_dpp v31, v31, v31 row_bcast:31 row_mask:0xc bank_mask:0xf
	v_add_f32_dpp v32, v32, v32 row_shr:1 row_mask:0xf bank_mask:0xf
	v_add_f32_dpp v33, v33, v33 row_shr:1 row_mask:0xf bank_mask:0xf
	v_add_f32_dpp v34, v34, v34 row_shr:1 row_mask:0xf bank_mask:0xf
	v_add_f32_dpp v35, v35, v35 row_shr:1 row_mask:0xf bank_mask:0xf
	v_add_f32_dpp v32, v32, v32 row_shr:2 row_mask:0xf bank_mask:0xf
	v_add_f32_dpp v33, v33, v33 row_shr:2 row_mask:0xf bank_mask:0xf
	v_add_f32_dpp v34, v34, v34 row_shr:2 row_mask:0xf bank_mask:0xf
	v_add_f32_dpp v35, v35, v35 row_shr:2 row_mask:0xf bank_mask:0xf
	v_add_f32_dpp v32, v32, v32 row_shr:4 row_mask:0xf bank_mask:0xf
	v_add_f32_dpp v33, v33, v33 row_shr:4 row_mask:0xf bank_mask:0xf
	v_add_f32_dpp v34, v34, v34 row_shr:4 row_mask:0xf bank_mask:0xf
	v_add_f32_dpp v35, v35, v35 row_shr:4 row_mask:0xf bank_mask:0xf
; DI void scan_unit(const Params& p, int su) {
;     ...
;         for (int i = 0; i < 65; ++i) { const int e = e0 + i; vals[i] = src[(size_t)(e < LP ? e : LP - 1) * 8]; }
;         float s = 0.f;
; #pragma unroll
;         for (int i = 0; i < 65; ++i) s += (e0 + i < LP) ? vals[i] : 0.f;
;         float incl = s;
; #pragma unroll
;         for (int o = 1; o < 64; o <<= 1) { const float t = __shfl_up(incl, o); if (lane >= o) incl += t; }
	v_add_f32_dpp v32, v32, v32 row_shr:8 row_mask:0xf bank_mask:0xf
	v_add_f32_dpp v33, v33, v33 row_shr:8 row_mask:0xf bank_mask:0xf
	v_add_f32_dpp v34, v34, v34 row_shr:8 row_mask:0xf bank_mask:0xf
	v_add_f32_dpp v35, v35, v35 row_shr:8 row_mask:0xf bank_mask:0xf
	v_add_f32_dpp v32, v32, v32 row_bcast:15 row_mask:0xa bank_mask:0xf
	v_add_f32_dpp v33, v33, v33 row_bcast:15 row_mask:0xa bank_mask:0xf
	v_add_f32_dpp v34, v34, v34 row_bcast:15 row_mask:0xa bank_mask:0xf
	v_add_f32_dpp v35, v35, v35 row_bcast:15 row_mask:0xa bank_mask:0xf
	v_add_f32_dpp v32, v32, v32 row_bcast:31 row_mask:0xc bank_mask:0xf
	v_add_f32_dpp v33, v33, v33 row_bcast:31 row_mask:0xc bank_mask:0xf
	v_add_f32_dpp v34, v34, v34 row_bcast:31 row_mask:0xc bank_mask:0xf
	v_add_f32_dpp v35, v35, v35 row_bcast:31 row_mask:0xc bank_mask:0xf
	v_add_f32_dpp v36, v36, v36 row_shr:1 row_mask:0xf bank_mask:0xf
	v_add_f32_dpp v37, v37, v37 row_shr:1 row_mask:0xf bank_mask:0xf
	v_add_f32_dpp v38, v38, v38 row_shr:1 row_mask:0xf bank_mask:0xf
	v_add_f32_dpp v39, v39, v39 row_shr:1 row_mask:0xf bank_mask:0xf
	v_add_f32_dpp v36, v36, v36 row_shr:2 row_mask:0xf bank_mask:0xf
	v_add_f32_dpp v37, v37, v37 row_shr:2 row_mask:0xf bank_mask:0xf
	v_add_f32_dpp v38, v38, v38 row_shr:2 row_mask:0xf bank_mask:0xf
	v_add_f32_dpp v39, v39, v39 row_shr:2 row_mask:0xf bank_mask:0xf
	v_add_f32_dpp v36, v36, v36 row_shr:4 row_mask:0xf bank_mask:0xf
	v_add_f32_dpp v37, v37, v37 row_shr:4 row_mask:0xf bank_mask:0xf
	v_add_f32_dpp v38, v38, v38 row_shr:4 row_mask:0xf bank_mask:0xf
	v_add_f32_dpp v39, v39, v39 row_shr:4 row_mask:0xf bank_mask:0xf
	v_add_f32_dpp v36, v36, v36 row_shr:8 row_mask:0xf bank_mask:0xf
	v_add_f32_dpp v37, v37, v37 row_shr:8 row_mask:0xf bank_mask:0xf
	v_add_f32_dpp v38, v38, v38 row_shr:8 row_mask:0xf bank_mask:0xf
	v_add_f32_dpp v39, v39, v39 row_shr:8 row_mask:0xf bank_mask:0xf
	v_add_f32_dpp v36, v36, v36 row_bcast:15 row_mask:0xa bank_mask:0xf
	v_add_f32_dpp v37, v37, v37 row_bcast:15 row_mask:0xa bank_mask:0xf
	v_add_f32_dpp v38, v38, v38 row_bcast:15 row_mask:0xa bank_mask:0xf
	v_add_f32_dpp v39, v39, v39 row_bcast:15 row_mask:0xa bank_mask:0xf
	v_add_f32_dpp v36, v36, v36 row_bcast:31 row_mask:0xc bank_mask:0xf
	v_add_f32_dpp v37, v37, v37 row_bcast:31 row_mask:0xc bank_mask:0xf
	v_add_f32_dpp v38, v38, v38 row_bcast:31 row_mask:0xc bank_mask:0xf
	v_add_f32_dpp v39, v39, v39 row_bcast:31 row_mask:0xc bank_mask:0xf
	v_add_f32_dpp v40, v40, v40 row_shr:1 row_mask:0xf bank_mask:0xf
	v_add_f32_dpp v41, v41, v41 row_shr:1 row_mask:0xf bank_mask:0xf
	v_add_f32_dpp v42, v42, v42 row_shr:1 row_mask:0xf bank_mask:0xf
	v_add_f32_dpp v43, v43, v43 row_shr:1 row_mask:0xf bank_mask:0xf
	v_add_f32_dpp v40, v40, v40 row_shr:2 row_mask:0xf bank_mask:0xf
	v_add_f32_dpp v41, v41, v41 row_shr:2 row_mask:0xf bank_mask:0xf
	v_add_f32_dpp v42, v42, v42 row_shr:2 row_mask:0xf bank_mask:0xf
	v_add_f32_dpp v43, v43, v43 row_shr:2 row_mask:0xf bank_mask:0xf
	v_add_f32_dpp v40, v40, v40 row_shr:4 row_mask:0xf bank_mask:0xf
	v_add_f32_dpp v41, v41, v41 row_shr:4 row_mask:0xf bank_mask:0xf
	v_add_f32_dpp v42, v42, v42 row_shr:4 row_mask:0xf bank_mask:0xf
	v_add_f32_dpp v43, v43, v43 row_shr:4 row_mask:0xf bank_mask:0xf
	v_add_f32_dpp v40, v40, v40 row_shr:8 row_mask:0xf bank_mask:0xf
	v_add_f32_dpp v41, v41, v41 row_shr:8 row_mask:0xf bank_mask:0xf
	v_add_f32_dpp v42, v42, v42 row_shr:8 row_mask:0xf bank_mask:0xf
	v_add_f32_dpp v43, v43, v43 row_shr:8 row_mask:0xf bank_mask:0xf
	v_add_f32_dpp v40, v40, v40 row_bcast:15 row_mask:0xa bank_mask:0xf
	v_add_f32_dpp v41, v41, v41 row_bcast:15 row_mask:0xa bank_mask:0xf
	v_add_f32_dpp v42, v42, v42 row_bcast:15 row_mask:0xa bank_mask:0xf
	v_add_f32_dpp v43, v43, v43 row_bcast:15 row_mask:0xa bank_mask:0xf
	v_add_f32_dpp v40, v40, v40 row_bcast:31 row_mask:0xc bank_mask:0xf
	v_add_f32_dpp v41, v41, v41 row_bcast:31 row_mask:0xc bank_mask:0xf
	v_add_f32_dpp v42, v42, v42 row_bcast:31 row_mask:0xc bank_mask:0xf
	v_add_f32_dpp v43, v43, v43 row_bcast:31 row_mask:0xc bank_mask:0xf
	v_add_f32_dpp v44, v44, v44 row_shr:1 row_mask:0xf bank_mask:0xf
	v_add_f32_dpp v45, v45, v45 row_shr:1 row_mask:0xf bank_mask:0xf
	v_add_f32_dpp v46, v46, v46 row_shr:1 row_mask:0xf bank_mask:0xf
	v_add_f32_dpp v47, v47, v47 row_shr:1 row_mask:0xf bank_mask:0xf
	v_add_f32_dpp v44, v44, v44 row_shr:2 row_mask:0xf bank_mask:0xf
	v_add_f32_dpp v45, v45, v45 row_shr:2 row_mask:0xf bank_mask:0xf
	v_add_f32_dpp v46, v46, v46 row_shr:2 row_mask:0xf bank_mask:0xf
	v_add_f32_dpp v47, v47, v47 row_shr:2 row_mask:0xf bank_mask:0xf
	v_add_f32_dpp v44, v44, v44 row_shr:4 row_mask:0xf bank_mask:0xf
	v_add_f32_dpp v45, v45, v45 row_shr:4 row_mask:0xf bank_mask:0xf
	v_add_f32_dpp v46, v46, v46 row_shr:4 row_mask:0xf bank_mask:0xf
	v_add_f32_dpp v47, v47, v47 row_shr:4 row_mask:0xf bank_mask:0xf
	v_add_f32_dpp v44, v44, v44 row_shr:8 row_mask:0xf bank_mask:0xf
	v_add_f32_dpp v45, v45, v45 row_shr:8 row_mask:0xf bank_mask:0xf
	v_add_f32_dpp v46, v46, v46 row_shr:8 row_mask:0xf bank_mask:0xf
	v_add_f32_dpp v47, v47, v47 row_shr:8 row_mask:0xf bank_mask:0xf
	v_add_f32_dpp v44, v44, v44 row_bcast:15 row_mask:0xa bank_mask:0xf
	v_add_f32_dpp v45, v45, v45 row_bcast:15 row_mask:0xa bank_mask:0xf
	v_add_f32_dpp v46, v46, v46 row_bcast:15 row_mask:0xa bank_mask:0xf
	v_add_f32_dpp v47, v47, v47 row_bcast:15 row_mask:0xa bank_mask:0xf
	v_add_f32_dpp v44, v44, v44 row_bcast:31 row_mask:0xc bank_mask:0xf
	v_add_f32_dpp v45, v45, v45 row_bcast:31 row_mask:0xc bank_mask:0xf
	v_add_f32_dpp v46, v46, v46 row_bcast:31 row_mask:0xc bank_mask:0xf
	v_add_f32_dpp v47, v47, v47 row_bcast:31 row_mask:0xc bank_mask:0xf
; DI void scan_unit(const Params& p, int su) {
;     ...
;         for (int i = 0; i < 65; ++i) { const int e = e0 + i; vals[i] = src[(size_t)(e < LP ? e : LP - 1) * 8]; }
;         float s = 0.f;
; #pragma unroll
;         for (int i = 0; i < 65; ++i) s += (e0 + i < LP) ? vals[i] : 0.f;
;         float incl = s;
; #pragma unroll
;         for (int o = 1; o < 64; o <<= 1) { const float t = __shfl_up(incl, o); if (lane >= o) incl += t; }
	v_add_f32_dpp v48, v48, v48 row_shr:1 row_mask:0xf bank_mask:0xf
	v_add_f32_dpp v49, v49, v49 row_shr:1 row_mask:0xf bank_mask:0xf
	v_add_f32_dpp v50, v50, v50 row_shr:1 row_mask:0xf bank_mask:0xf
	v_add_f32_dpp v51, v51, v51 row_shr:1 row_mask:0xf bank_mask:0xf
	v_add_f32_dpp v48, v48, v48 row_shr:2 row_mask:0xf bank_mask:0xf
	v_add_f32_dpp v49, v49, v49 row_shr:2 row_mask:0xf bank_mask:0xf
	v_add_f32_dpp v50, v50, v50 row_shr:2 row_mask:0xf bank_mask:0xf
	v_add_f32_dpp v51, v51, v51 row_shr:2 row_mask:0xf bank_mask:0xf
	v_add_f32_dpp v48, v48, v48 row_shr:4 row_mask:0xf bank_mask:0xf
	v_add_f32_dpp v49, v49, v49 row_shr:4 row_mask:0xf bank_mask:0xf
	v_add_f32_dpp v50, v50, v50 row_shr:4 row_mask:0xf bank_mask:0xf
	v_add_f32_dpp v51, v51, v51 row_shr:4 row_mask:0xf bank_mask:0xf
	v_add_f32_dpp v48, v48, v48 row_shr:8 row_mask:0xf bank_mask:0xf
	v_add_f32_dpp v49, v49, v49 row_shr:8 row_mask:0xf bank_mask:0xf
	v_add_f32_dpp v50, v50, v50 row_shr:8 row_mask:0xf bank_mask:0xf
	v_add_f32_dpp v51, v51, v51 row_shr:8 row_mask:0xf bank_mask:0xf
	v_add_f32_dpp v48, v48, v48 row_bcast:15 row_mask:0xa bank_mask:0xf
	v_add_f32_dpp v49, v49, v49 row_bcast:15 row_mask:0xa bank_mask:0xf
	v_add_f32_dpp v50, v50, v50 row_bcast:15 row_mask:0xa bank_mask:0xf
	v_add_f32_dpp v51, v51, v51 row_bcast:15 row_mask:0xa bank_mask:0xf
	v_add_f32_dpp v48, v48, v48 row_bcast:31 row_mask:0xc bank_mask:0xf
	v_add_f32_dpp v49, v49, v49 row_bcast:31 row_mask:0xc bank_mask:0xf
	v_add_f32_dpp v50, v50, v50 row_bcast:31 row_mask:0xc bank_mask:0xf
	v_add_f32_dpp v51, v51, v51 row_bcast:31 row_mask:0xc bank_mask:0xf
	v_add_f32_dpp v52, v52, v52 row_shr:1 row_mask:0xf bank_mask:0xf
	v_add_f32_dpp v53, v53, v53 row_shr:1 row_mask:0xf bank_mask:0xf
	v_add_f32_dpp v54, v54, v54 row_shr:1 row_mask:0xf bank_mask:0xf
	v_add_f32_dpp v55, v55, v55 row_shr:1 row_mask:0xf bank_mask:0xf
	v_add_f32_dpp v52, v52, v52 row_shr:2 row_mask:0xf bank_mask:0xf
	v_add_f32_dpp v53, v53, v53 row_shr:2 row_mask:0xf bank_mask:0xf
	v_add_f32_dpp v54, v54, v54 row_shr:2 row_mask:0xf bank_mask:0xf
	v_add_f32_dpp v55, v55, v55 row_shr:2 row_mask:0xf bank_mask:0xf
	v_add_f32_dpp v52, v52, v52 row_shr:4 row_mask:0xf bank_mask:0xf
	v_add_f32_dpp v53, v53, v53 row_shr:4 row_mask:0xf bank_mask:0xf
	v_add_f32_dpp v54, v54, v54 row_shr:4 row_mask:0xf bank_mask:0xf
	v_add_f32_dpp v55, v55, v55 row_shr:4 row_mask:0xf bank_mask:0xf
	v_add_f32_dpp v52, v52, v52 row_shr:8 row_mask:0xf bank_mask:0xf
	v_add_f32_dpp v53, v53, v53 row_shr:8 row_mask:0xf bank_mask:0xf
	v_add_f32_dpp v54, v54, v54 row_shr:8 row_mask:0xf bank_mask:0xf
	v_add_f32_dpp v55, v55, v55 row_shr:8 row_mask:0xf bank_mask:0xf
	v_add_f32_dpp v52, v52, v52 row_bcast:15 row_mask:0xa bank_mask:0xf
	v_add_f32_dpp v53, v53, v53 row_bcast:15 row_mask:0xa bank_mask:0xf
	v_add_f32_dpp v54, v54, v54 row_bcast:15 row_mask:0xa bank_mask:0xf
	v_add_f32_dpp v55, v55, v55 row_bcast:15 row_mask:0xa bank_mask:0xf
	v_add_f32_dpp v52, v52, v52 row_bcast:31 row_mask:0xc bank_mask:0xf
	v_add_f32_dpp v53, v53, v53 row_bcast:31 row_mask:0xc bank_mask:0xf
	v_add_f32_dpp v54, v54, v54 row_bcast:31 row_mask:0xc bank_mask:0xf
	v_add_f32_dpp v55, v55, v55 row_bcast:31 row_mask:0xc bank_mask:0xf
	v_add_f32_dpp v56, v56, v56 row_shr:1 row_mask:0xf bank_mask:0xf
	v_add_f32_dpp v57, v57, v57 row_shr:1 row_mask:0xf bank_mask:0xf
	v_add_f32_dpp v58, v58, v58 row_shr:1 row_mask:0xf bank_mask:0xf
	v_add_f32_dpp v59, v59, v59 row_shr:1 row_mask:0xf bank_mask:0xf
	v_add_f32_dpp v56, v56, v56 row_shr:2 row_mask:0xf bank_mask:0xf
	v_add_f32_dpp v57, v57, v57 row_shr:2 row_mask:0xf bank_mask:0xf
	v_add_f32_dpp v58, v58, v58 row_shr:2 row_mask:0xf bank_mask:0xf
	v_add_f32_dpp v59, v59, v59 row_shr:2 row_mask:0xf bank_mask:0xf
	v_add_f32_dpp v56, v56, v56 row_shr:4 row_mask:0xf bank_mask:0xf
	v_add_f32_dpp v57, v57, v57 row_shr:4 row_mask:0xf bank_mask:0xf
	v_add_f32_dpp v58, v58, v58 row_shr:4 row_mask:0xf bank_mask:0xf
	v_add_f32_dpp v59, v59, v59 row_shr:4 row_mask:0xf bank_mask:0xf
	v_add_f32_dpp v56, v56, v56 row_shr:8 row_mask:0xf bank_mask:0xf
	v_add_f32_dpp v57, v57, v57 row_shr:8 row_mask:0xf bank_mask:0xf
	v_add_f32_dpp v58, v58, v58 row_shr:8 row_mask:0xf bank_mask:0xf
	v_add_f32_dpp v59, v59, v59 row_shr:8 row_mask:0xf bank_mask:0xf
	v_add_f32_dpp v56, v56, v56 row_bcast:15 row_mask:0xa bank_mask:0xf
	v_add_f32_dpp v57, v57, v57 row_bcast:15 row_mask:0xa bank_mask:0xf
	v_add_f32_dpp v58, v58, v58 row_bcast:15 row_mask:0xa bank_mask:0xf
	v_add_f32_dpp v59, v59, v59 row_bcast:15 row_mask:0xa bank_mask:0xf
	v_add_f32_dpp v56, v56, v56 row_bcast:31 row_mask:0xc bank_mask:0xf
	v_add_f32_dpp v57, v57, v57 row_bcast:31 row_mask:0xc bank_mask:0xf
	v_add_f32_dpp v58, v58, v58 row_bcast:31 row_mask:0xc bank_mask:0xf
	v_add_f32_dpp v59, v59, v59 row_bcast:31 row_mask:0xc bank_mask:0xf
	v_add_f32_dpp v60, v60, v60 row_shr:1 row_mask:0xf bank_mask:0xf
	v_add_f32_dpp v61, v61, v61 row_shr:1 row_mask:0xf bank_mask:0xf
	v_add_f32_dpp v62, v62, v62 row_shr:1 row_mask:0xf bank_mask:0xf
	v_add_f32_dpp v63, v63, v63 row_shr:1 row_mask:0xf bank_mask:0xf
	v_add_f32_dpp v60, v60, v60 row_shr:2 row_mask:0xf bank_mask:0xf
	v_add_f32_dpp v61, v61, v61 row_shr:2 row_mask:0xf bank_mask:0xf
	v_add_f32_dpp v62, v62, v62 row_shr:2 row_mask:0xf bank_mask:0xf
	v_add_f32_dpp v63, v63, v63 row_shr:2 row_mask:0xf bank_mask:0xf
	v_add_f32_dpp v60, v60, v60 row_shr:4 row_mask:0xf bank_mask:0xf
	v_add_f32_dpp v61, v61, v61 row_shr:4 row_mask:0xf bank_mask:0xf
	v_add_f32_dpp v62, v62, v62 row_shr:4 row_mask:0xf bank_mask:0xf
	v_add_f32_dpp v63, v63, v63 row_shr:4 row_mask:0xf bank_mask:0xf
; DI void scan_unit(const Params& p, int su) {
;     ...
;         for (int i = 0; i < 65; ++i) { const int e = e0 + i; vals[i] = src[(size_t)(e < LP ? e : LP - 1) * 8]; }
;         float s = 0.f;
; #pragma unroll
;         for (int i = 0; i < 65; ++i) s += (e0 + i < LP) ? vals[i] : 0.f;
;         float incl = s;
; #pragma unroll
;         for (int o = 1; o < 64; o <<= 1) { const float t = __shfl_up(incl, o); if (lane >= o) incl += t; }
	v_add_f32_dpp v60, v60, v60 row_shr:8 row_mask:0xf bank_mask:0xf
	v_add_f32_dpp v61, v61, v61 row_shr:8 row_mask:0xf bank_mask:0xf
	v_add_f32_dpp v62, v62, v62 row_shr:8 row_mask:0xf bank_mask:0xf
	v_add_f32_dpp v63, v63, v63 row_shr:8 row_mask:0xf bank_mask:0xf
	v_add_f32_dpp v60, v60, v60 row_bcast:15 row_mask:0xa bank_mask:0xf
	v_add_f32_dpp v61, v61, v61 row_bcast:15 row_mask:0xa bank_mask:0xf
	v_add_f32_dpp v62, v62, v62 row_bcast:15 row_mask:0xa bank_mask:0xf
	v_add_f32_dpp v63, v63, v63 row_bcast:15 row_mask:0xa bank_mask:0xf
	v_add_f32_dpp v60, v60, v60 row_bcast:31 row_mask:0xc bank_mask:0xf
	v_add_f32_dpp v61, v61, v61 row_bcast:31 row_mask:0xc bank_mask:0xf
	v_add_f32_dpp v62, v62, v62 row_bcast:31 row_mask:0xc bank_mask:0xf
	v_add_f32_dpp v63, v63, v63 row_bcast:31 row_mask:0xc bank_mask:0xf
	v_add_f32_dpp v64, v64, v64 row_shr:1 row_mask:0xf bank_mask:0xf
	v_add_f32_dpp v65, v65, v65 row_shr:1 row_mask:0xf bank_mask:0xf
	v_add_f32_dpp v66, v66, v66 row_shr:1 row_mask:0xf bank_mask:0xf
	v_add_f32_dpp v67, v67, v67 row_shr:1 row_mask:0xf bank_mask:0xf
	v_add_f32_dpp v64, v64, v64 row_shr:2 row_mask:0xf bank_mask:0xf
	v_add_f32_dpp v65, v65, v65 row_shr:2 row_mask:0xf bank_mask:0xf
	v_add_f32_dpp v66, v66, v66 row_shr:2 row_mask:0xf bank_mask:0xf
	v_add_f32_dpp v67, v67, v67 row_shr:2 row_mask:0xf bank_mask:0xf
	v_add_f32_dpp v64, v64, v64 row_shr:4 row_mask:0xf bank_mask:0xf
	v_add_f32_dpp v65, v65, v65 row_shr:4 row_mask:0xf bank_mask:0xf
	v_add_f32_dpp v66, v66, v66 row_shr:4 row_mask:0xf bank_mask:0xf
	v_add_f32_dpp v67, v67, v67 row_shr:4 row_mask:0xf bank_mask:0xf
	v_add_f32_dpp v64, v64, v64 row_shr:8 row_mask:0xf bank_mask:0xf
	v_add_f32_dpp v65, v65, v65 row_shr:8 row_mask:0xf bank_mask:0xf
	v_add_f32_dpp v66, v66, v66 row_shr:8 row_mask:0xf bank_mask:0xf
	v_add_f32_dpp v67, v67, v67 row_shr:8 row_mask:0xf bank_mask:0xf
	v_add_f32_dpp v64, v64, v64 row_bcast:15 row_mask:0xa bank_mask:0xf
	v_add_f32_dpp v65, v65, v65 row_bcast:15 row_mask:0xa bank_mask:0xf
	v_add_f32_dpp v66, v66, v66 row_bcast:15 row_mask:0xa bank_mask:0xf
	v_add_f32_dpp v67, v67, v67 row_bcast:15 row_mask:0xa bank_mask:0xf
	v_add_f32_dpp v64, v64, v64 row_bcast:31 row_mask:0xc bank_mask:0xf
	v_add_f32_dpp v65, v65, v65 row_bcast:31 row_mask:0xc bank_mask:0xf
	v_add_f32_dpp v66, v66, v66 row_bcast:31 row_mask:0xc bank_mask:0xf
	v_add_f32_dpp v67, v67, v67 row_bcast:31 row_mask:0xc bank_mask:0xf
	v_add_f32_dpp v68, v68, v68 row_shr:1 row_mask:0xf bank_mask:0xf
	v_add_f32_dpp v69, v69, v69 row_shr:1 row_mask:0xf bank_mask:0xf
	v_add_f32_dpp v70, v70, v70 row_shr:1 row_mask:0xf bank_mask:0xf
	v_add_f32_dpp v71, v71, v71 row_shr:1 row_mask:0xf bank_mask:0xf
	v_add_f32_dpp v68, v68, v68 row_shr:2 row_mask:0xf bank_mask:0xf
	v_add_f32_dpp v69, v69, v69 row_shr:2 row_mask:0xf bank_mask:0xf
	v_add_f32_dpp v70, v70, v70 row_shr:2 row_mask:0xf bank_mask:0xf
	v_add_f32_dpp v71, v71, v71 row_shr:2 row_mask:0xf bank_mask:0xf
	v_add_f32_dpp v68, v68, v68 row_shr:4 row_mask:0xf bank_mask:0xf
	v_add_f32_dpp v69, v69, v69 row_shr:4 row_mask:0xf bank_mask:0xf
	v_add_f32_dpp v70, v70, v70 row_shr:4 row_mask:0xf bank_mask:0xf
	v_add_f32_dpp v71, v71, v71 row_shr:4 row_mask:0xf bank_mask:0xf
	v_add_f32_dpp v68, v68, v68 row_shr:8 row_mask:0xf bank_mask:0xf
	v_add_f32_dpp v69, v69, v69 row_shr:8 row_mask:0xf bank_mask:0xf
	v_add_f32_dpp v70, v70, v70 row_shr:8 row_mask:0xf bank_mask:0xf
	v_add_f32_dpp v71, v71, v71 row_shr:8 row_mask:0xf bank_mask:0xf
	v_add_f32_dpp v68, v68, v68 row_bcast:15 row_mask:0xa bank_mask:0xf
	v_add_f32_dpp v69, v69, v69 row_bcast:15 row_mask:0xa bank_mask:0xf
	v_add_f32_dpp v70, v70, v70 row_bcast:15 row_mask:0xa bank_mask:0xf
	v_add_f32_dpp v71, v71, v71 row_bcast:15 row_mask:0xa bank_mask:0xf
	v_add_f32_dpp v68, v68, v68 row_bcast:31 row_mask:0xc bank_mask:0xf
	v_add_f32_dpp v69, v69, v69 row_bcast:31 row_mask:0xc bank_mask:0xf
	v_add_f32_dpp v70, v70, v70 row_bcast:31 row_mask:0xc bank_mask:0xf
	v_add_f32_dpp v71, v71, v71 row_bcast:31 row_mask:0xc bank_mask:0xf
	v_add_f32_dpp v72, v72, v72 row_shr:1 row_mask:0xf bank_mask:0xf
	v_add_f32_dpp v73, v73, v73 row_shr:1 row_mask:0xf bank_mask:0xf
	v_add_f32_dpp v74, v74, v74 row_shr:1 row_mask:0xf bank_mask:0xf
	v_add_f32_dpp v75, v75, v75 row_shr:1 row_mask:0xf bank_mask:0xf
	v_add_f32_dpp v72, v72, v72 row_shr:2 row_mask:0xf bank_mask:0xf
	v_add_f32_dpp v73, v73, v73 row_shr:2 row_mask:0xf bank_mask:0xf
	v_add_f32_dpp v74, v74, v74 row_shr:2 row_mask:0xf bank_mask:0xf
	v_add_f32_dpp v75, v75, v75 row_shr:2 row_mask:0xf bank_mask:0xf
	v_add_f32_dpp v72, v72, v72 row_shr:4 row_mask:0xf bank_mask:0xf
	v_add_f32_dpp v73, v73, v73 row_shr:4 row_mask:0xf bank_mask:0xf
	v_add_f32_dpp v74, v74, v74 row_shr:4 row_mask:0xf bank_mask:0xf
	v_add_f32_dpp v75, v75, v75 row_shr:4 row_mask:0xf bank_mask:0xf
	v_add_f32_dpp v72, v72, v72 row_shr:8 row_mask:0xf bank_mask:0xf
	v_add_f32_dpp v73, v73, v73 row_shr:8 row_mask:0xf bank_mask:0xf
	v_add_f32_dpp v74, v74, v74 row_shr:8 row_mask:0xf bank_mask:0xf
	v_add_f32_dpp v75, v75, v75 row_shr:8 row_mask:0xf bank_mask:0xf
	v_add_f32_dpp v72, v72, v72 row_bcast:15 row_mask:0xa bank_mask:0xf
	v_add_f32_dpp v73, v73, v73 row_bcast:15 row_mask:0xa bank_mask:0xf
	v_add_f32_dpp v74, v74, v74 row_bcast:15 row_mask:0xa bank_mask:0xf
	v_add_f32_dpp v75, v75, v75 row_bcast:15 row_mask:0xa bank_mask:0xf
	v_add_f32_dpp v72, v72, v72 row_bcast:31 row_mask:0xc bank_mask:0xf
	v_add_f32_dpp v73, v73, v73 row_bcast:31 row_mask:0xc bank_mask:0xf
	v_add_f32_dpp v74, v74, v74 row_bcast:31 row_mask:0xc bank_mask:0xf
	v_add_f32_dpp v75, v75, v75 row_bcast:31 row_mask:0xc bank_mask:0xf
; DI void scan_unit(const Params& p, int su) {
;     ...
;         float incl = s;
; #pragma unroll
;         for (int o = 1; o < 64; o <<= 1) { const float t = __shfl_up(incl, o); if (lane >= o) incl += t; }
;         float run = incl - s;
; #pragma unroll
;         for (int i = 0; i < 65; ++i) { const int e = e0 + i; if (e < LP) { run += vals[i]; dst[e] = run * LOG2E; } else dst[e] = 0.f; }
	v_add_f32_dpp v76, v76, v76 row_shr:1 row_mask:0xf bank_mask:0xf
	v_add_f32_dpp v77, v77, v77 row_shr:1 row_mask:0xf bank_mask:0xf
	v_add_f32_dpp v78, v78, v78 row_shr:1 row_mask:0xf bank_mask:0xf
	v_add_f32_dpp v79, v79, v79 row_shr:1 row_mask:0xf bank_mask:0xf
	v_add_f32_dpp v76, v76, v76 row_shr:2 row_mask:0xf bank_mask:0xf
	v_add_f32_dpp v77, v77, v77 row_shr:2 row_mask:0xf bank_mask:0xf
	v_add_f32_dpp v78, v78, v78 row_shr:2 row_mask:0xf bank_mask:0xf
	v_add_f32_dpp v79, v79, v79 row_shr:2 row_mask:0xf bank_mask:0xf
	v_add_f32_dpp v76, v76, v76 row_shr:4 row_mask:0xf bank_mask:0xf
	v_add_f32_dpp v77, v77, v77 row_shr:4 row_mask:0xf bank_mask:0xf
	v_add_f32_dpp v78, v78, v78 row_shr:4 row_mask:0xf bank_mask:0xf
	v_add_f32_dpp v79, v79, v79 row_shr:4 row_mask:0xf bank_mask:0xf
	v_add_f32_dpp v76, v76, v76 row_shr:8 row_mask:0xf bank_mask:0xf
	v_add_f32_dpp v77, v77, v77 row_shr:8 row_mask:0xf bank_mask:0xf
	v_add_f32_dpp v78, v78, v78 row_shr:8 row_mask:0xf bank_mask:0xf
	v_add_f32_dpp v79, v79, v79 row_shr:8 row_mask:0xf bank_mask:0xf
	v_add_f32_dpp v76, v76, v76 row_bcast:15 row_mask:0xa bank_mask:0xf
	v_add_f32_dpp v77, v77, v77 row_bcast:15 row_mask:0xa bank_mask:0xf
	v_add_f32_dpp v78, v78, v78 row_bcast:15 row_mask:0xa bank_mask:0xf
	v_add_f32_dpp v79, v79, v79 row_bcast:15 row_mask:0xa bank_mask:0xf
	v_add_f32_dpp v76, v76, v76 row_bcast:31 row_mask:0xc bank_mask:0xf
	v_add_f32_dpp v77, v77, v77 row_bcast:31 row_mask:0xc bank_mask:0xf
	v_add_f32_dpp v78, v78, v78 row_bcast:31 row_mask:0xc bank_mask:0xf
	v_add_f32_dpp v79, v79, v79 row_bcast:31 row_mask:0xc bank_mask:0xf
	v_add_f32_dpp v80, v80, v80 row_shr:1 row_mask:0xf bank_mask:0xf
	v_add_f32_dpp v81, v81, v81 row_shr:1 row_mask:0xf bank_mask:0xf
	v_add_f32_dpp v82, v82, v82 row_shr:1 row_mask:0xf bank_mask:0xf
	v_add_f32_dpp v83, v83, v83 row_shr:1 row_mask:0xf bank_mask:0xf
	v_add_f32_dpp v80, v80, v80 row_shr:2 row_mask:0xf bank_mask:0xf
	v_add_f32_dpp v81, v81, v81 row_shr:2 row_mask:0xf bank_mask:0xf
	v_add_f32_dpp v82, v82, v82 row_shr:2 row_mask:0xf bank_mask:0xf
	v_add_f32_dpp v83, v83, v83 row_shr:2 row_mask:0xf bank_mask:0xf
	v_add_f32_dpp v80, v80, v80 row_shr:4 row_mask:0xf bank_mask:0xf
	v_add_f32_dpp v81, v81, v81 row_shr:4 row_mask:0xf bank_mask:0xf
	v_add_f32_dpp v82, v82, v82 row_shr:4 row_mask:0xf bank_mask:0xf
	v_add_f32_dpp v83, v83, v83 row_shr:4 row_mask:0xf bank_mask:0xf
	v_add_f32_dpp v80, v80, v80 row_shr:8 row_mask:0xf bank_mask:0xf
	v_add_f32_dpp v81, v81, v81 row_shr:8 row_mask:0xf bank_mask:0xf
	v_add_f32_dpp v82, v82, v82 row_shr:8 row_mask:0xf bank_mask:0xf
	v_add_f32_dpp v83, v83, v83 row_shr:8 row_mask:0xf bank_mask:0xf
	v_add_f32_dpp v80, v80, v80 row_bcast:15 row_mask:0xa bank_mask:0xf
	v_add_f32_dpp v81, v81, v81 row_bcast:15 row_mask:0xa bank_mask:0xf
	v_add_f32_dpp v82, v82, v82 row_bcast:15 row_mask:0xa bank_mask:0xf
	v_add_f32_dpp v83, v83, v83 row_bcast:15 row_mask:0xa bank_mask:0xf
	v_add_f32_dpp v80, v80, v80 row_bcast:31 row_mask:0xc bank_mask:0xf
	v_add_f32_dpp v81, v81, v81 row_bcast:31 row_mask:0xc bank_mask:0xf
	v_add_f32_dpp v82, v82, v82 row_bcast:31 row_mask:0xc bank_mask:0xf
	v_add_f32_dpp v83, v83, v83 row_bcast:31 row_mask:0xc bank_mask:0xf
	v_add_f32_dpp v84, v84, v84 row_shr:1 row_mask:0xf bank_mask:0xf
	s_nop 0
	s_nop 0
	s_nop 0
	v_add_f32_dpp v84, v84, v84 row_shr:2 row_mask:0xf bank_mask:0xf
	s_nop 0
	s_nop 0
	s_nop 0
	v_add_f32_dpp v84, v84, v84 row_shr:4 row_mask:0xf bank_mask:0xf
	s_nop 0
	s_nop 0
	s_nop 0
	v_add_f32_dpp v84, v84, v84 row_shr:8 row_mask:0xf bank_mask:0xf
	s_nop 0
	s_nop 0
	s_nop 0
	v_add_f32_dpp v84, v84, v84 row_bcast:15 row_mask:0xa bank_mask:0xf
	s_nop 0
	s_nop 0
	s_nop 0
	v_add_f32_dpp v84, v84, v84 row_bcast:31 row_mask:0xc bank_mask:0xf
	s_nop 0
	s_nop 0
	s_nop 0
	s_nop 1
	v_readlane_b32 s0, v20, 63
	s_nop 1
	v_add_f32_e32 v21, s0, v21
	s_nop 0
	v_readlane_b32 s0, v21, 63
	s_nop 1
	v_add_f32_e32 v22, s0, v22
	s_nop 0
	v_readlane_b32 s0, v22, 63
	s_nop 1
	v_add_f32_e32 v23, s0, v23
	s_nop 0
	v_readlane_b32 s0, v23, 63
	s_nop 1
	v_add_f32_e32 v24, s0, v24
	s_nop 0
	v_readlane_b32 s0, v24, 63
	s_nop 1
	v_add_f32_e32 v25, s0, v25
	s_nop 0
	v_readlane_b32 s0, v25, 63
	s_nop 1
	v_add_f32_e32 v26, s0, v26
	s_nop 0
	v_readlane_b32 s0, v26, 63
	s_nop 1
	v_add_f32_e32 v27, s0, v27
	s_nop 0
	v_readlane_b32 s0, v27, 63
	s_nop 1
	v_add_f32_e32 v28, s0, v28
	s_nop 0
	v_readlane_b32 s0, v28, 63
	s_nop 1
	v_add_f32_e32 v29, s0, v29
	s_nop 0
	v_readlane_b32 s0, v29, 63
	s_nop 1
	v_add_f32_e32 v30, s0, v30
	s_nop 0
	v_readlane_b32 s0, v30, 63
	s_nop 1
	v_add_f32_e32 v31, s0, v31
	s_nop 0
	v_readlane_b32 s0, v31, 63
	s_nop 1
	v_add_f32_e32 v32, s0, v32
	s_nop 0
	v_readlane_b32 s0, v32, 63
	s_nop 1
	v_add_f32_e32 v33, s0, v33
	s_nop 0
	v_readlane_b32 s0, v33, 63
	s_nop 1
	v_add_f32_e32 v34, s0, v34
	s_nop 0
	v_readlane_b32 s0, v34, 63
	s_nop 1
	v_add_f32_e32 v35, s0, v35
	s_nop 0
	v_readlane_b32 s0, v35, 63
	s_nop 1
	v_add_f32_e32 v36, s0, v36
	s_nop 0
	v_readlane_b32 s0, v36, 63
	s_nop 1
	v_add_f32_e32 v37, s0, v37
	s_nop 0
	v_readlane_b32 s0, v37, 63
	s_nop 1
	v_add_f32_e32 v38, s0, v38
	s_nop 0
	v_readlane_b32 s0, v38, 63
	s_nop 1
	v_add_f32_e32 v39, s0, v39
	s_nop 0
	v_readlane_b32 s0, v39, 63
	s_nop 1
	v_add_f32_e32 v40, s0, v40
	s_nop 0
	v_readlane_b32 s0, v40, 63
	s_nop 1
	v_add_f32_e32 v41, s0, v41
	s_nop 0
	v_readlane_b32 s0, v41, 63
	s_nop 1
	v_add_f32_e32 v42, s0, v42
	s_nop 0
	v_readlane_b32 s0, v42, 63
	s_nop 1
	v_add_f32_e32 v43, s0, v43
	s_nop 0
	v_readlane_b32 s0, v43, 63
	s_nop 1
	v_add_f32_e32 v44, s0, v44
	s_nop 0
	v_readlane_b32 s0, v44, 63
	s_nop 1
	v_add_f32_e32 v45, s0, v45
	s_nop 0
; DI void scan_unit(const Params& p, int su) {
;     ...
;         float run = incl - s;
; #pragma unroll
;         for (int i = 0; i < 65; ++i) { const int e = e0 + i; if (e < LP) { run += vals[i]; dst[e] = run * LOG2E; } else dst[e] = 0.f; }
	v_readlane_b32 s0, v45, 63
	s_nop 1
	v_add_f32_e32 v46, s0, v46
	s_nop 0
	v_readlane_b32 s0, v46, 63
	s_nop 1
	v_add_f32_e32 v47, s0, v47
	s_nop 0
	v_readlane_b32 s0, v47, 63
	s_nop 1
	v_add_f32_e32 v48, s0, v48
	s_nop 0
	v_readlane_b32 s0, v48, 63
	s_nop 1
	v_add_f32_e32 v49, s0, v49
	s_nop 0
	v_readlane_b32 s0, v49, 63
	s_nop 1
	v_add_f32_e32 v50, s0, v50
	s_nop 0
	v_readlane_b32 s0, v50, 63
	s_nop 1
	v_add_f32_e32 v51, s0, v51
	s_nop 0
	v_readlane_b32 s0, v51, 63
	s_nop 1
	v_add_f32_e32 v52, s0, v52
	s_nop 0
	v_readlane_b32 s0, v52, 63
	s_nop 1
	v_add_f32_e32 v53, s0, v53
	s_nop 0
	v_readlane_b32 s0, v53, 63
	s_nop 1
	v_add_f32_e32 v54, s0, v54
	s_nop 0
	v_readlane_b32 s0, v54, 63
	s_nop 1
	v_add_f32_e32 v55, s0, v55
	s_nop 0
	v_readlane_b32 s0, v55, 63
	s_nop 1
	v_add_f32_e32 v56, s0, v56
	s_nop 0
	v_readlane_b32 s0, v56, 63
	s_nop 1
	v_add_f32_e32 v57, s0, v57
	s_nop 0
	v_readlane_b32 s0, v57, 63
	s_nop 1
	v_add_f32_e32 v58, s0, v58
	s_nop 0
	v_readlane_b32 s0, v58, 63
	s_nop 1
	v_add_f32_e32 v59, s0, v59
	s_nop 0
	v_readlane_b32 s0, v59, 63
	s_nop 1
	v_add_f32_e32 v60, s0, v60
	s_nop 0
	v_readlane_b32 s0, v60, 63
	s_nop 1
	v_add_f32_e32 v61, s0, v61
	s_nop 0
	v_readlane_b32 s0, v61, 63
	s_nop 1
	v_add_f32_e32 v62, s0, v62
	s_nop 0
	v_readlane_b32 s0, v62, 63
	s_nop 1
	v_add_f32_e32 v63, s0, v63
	s_nop 0
	v_readlane_b32 s0, v63, 63
	s_nop 1
	v_add_f32_e32 v64, s0, v64
	s_nop 0
	v_readlane_b32 s0, v64, 63
	s_nop 1
	v_add_f32_e32 v65, s0, v65
	s_nop 0
	v_readlane_b32 s0, v65, 63
	s_nop 1
	v_add_f32_e32 v66, s0, v66
	s_nop 0
	v_readlane_b32 s0, v66, 63
	s_nop 1
	v_add_f32_e32 v67, s0, v67
	s_nop 0
	v_readlane_b32 s0, v67, 63
	s_nop 1
	v_add_f32_e32 v68, s0, v68
	s_nop 0
	v_readlane_b32 s0, v68, 63
	s_nop 1
	v_add_f32_e32 v69, s0, v69
	s_nop 0
	v_readlane_b32 s0, v69, 63
	s_nop 1
	v_add_f32_e32 v70, s0, v70
	s_nop 0
	v_readlane_b32 s0, v70, 63
	s_nop 1
	v_add_f32_e32 v71, s0, v71
	s_nop 0
	v_readlane_b32 s0, v71, 63
	s_nop 1
	v_add_f32_e32 v72, s0, v72
	s_nop 0
	v_readlane_b32 s0, v72, 63
	s_nop 1
	v_add_f32_e32 v73, s0, v73
	s_nop 0
	v_readlane_b32 s0, v73, 63
	s_nop 1
	v_add_f32_e32 v74, s0, v74
	s_nop 0
	v_readlane_b32 s0, v74, 63
	s_nop 1
	v_add_f32_e32 v75, s0, v75
	s_nop 0
	v_readlane_b32 s0, v75, 63
	s_nop 1
	v_add_f32_e32 v76, s0, v76
	s_nop 0
	v_readlane_b32 s0, v76, 63
	s_nop 1
	v_add_f32_e32 v77, s0, v77
	s_nop 0
	v_readlane_b32 s0, v77, 63
	s_nop 1
	v_add_f32_e32 v78, s0, v78
	s_nop 0
	v_readlane_b32 s0, v78, 63
	s_nop 1
	v_add_f32_e32 v79, s0, v79
	s_nop 0
	v_readlane_b32 s0, v79, 63
	s_nop 1
	v_add_f32_e32 v80, s0, v80
	s_nop 0
	v_readlane_b32 s0, v80, 63
	s_nop 1
	v_add_f32_e32 v81, s0, v81
	s_nop 0
	v_readlane_b32 s0, v81, 63
	s_nop 1
	v_add_f32_e32 v82, s0, v82
	s_nop 0
	v_readlane_b32 s0, v82, 63
	s_nop 1
	v_add_f32_e32 v83, s0, v83
	s_nop 0
	v_readlane_b32 s0, v83, 63
	s_nop 1
	v_add_f32_e32 v84, s0, v84
	v_mul_f32_e32 v20, 0x3fb8aa3b, v20
	v_mul_f32_e32 v21, 0x3fb8aa3b, v21
	v_mul_f32_e32 v22, 0x3fb8aa3b, v22
	v_mul_f32_e32 v23, 0x3fb8aa3b, v23
	v_mul_f32_e32 v24, 0x3fb8aa3b, v24
	v_mul_f32_e32 v25, 0x3fb8aa3b, v25
	v_mul_f32_e32 v26, 0x3fb8aa3b, v26
	v_mul_f32_e32 v27, 0x3fb8aa3b, v27
	v_mul_f32_e32 v28, 0x3fb8aa3b, v28
	v_mul_f32_e32 v29, 0x3fb8aa3b, v29
	v_mul_f32_e32 v30, 0x3fb8aa3b, v30
	v_mul_f32_e32 v31, 0x3fb8aa3b, v31
	v_mul_f32_e32 v32, 0x3fb8aa3b, v32
	v_mul_f32_e32 v33, 0x3fb8aa3b, v33
	v_mul_f32_e32 v34, 0x3fb8aa3b, v34
	v_mul_f32_e32 v35, 0x3fb8aa3b, v35
	v_mul_f32_e32 v36, 0x3fb8aa3b, v36
	v_mul_f32_e32 v37, 0x3fb8aa3b, v37
	v_mul_f32_e32 v38, 0x3fb8aa3b, v38
	v_mul_f32_e32 v39, 0x3fb8aa3b, v39
	v_mul_f32_e32 v40, 0x3fb8aa3b, v40
	v_mul_f32_e32 v41, 0x3fb8aa3b, v41
	v_mul_f32_e32 v42, 0x3fb8aa3b, v42
	v_mul_f32_e32 v43, 0x3fb8aa3b, v43
	v_mul_f32_e32 v44, 0x3fb8aa3b, v44
	v_mul_f32_e32 v45, 0x3fb8aa3b, v45
	v_mul_f32_e32 v46, 0x3fb8aa3b, v46
	v_mul_f32_e32 v47, 0x3fb8aa3b, v47
	v_mul_f32_e32 v48, 0x3fb8aa3b, v48
	v_mul_f32_e32 v49, 0x3fb8aa3b, v49
	v_mul_f32_e32 v50, 0x3fb8aa3b, v50
	v_mul_f32_e32 v51, 0x3fb8aa3b, v51
	v_mul_f32_e32 v52, 0x3fb8aa3b, v52
	v_mul_f32_e32 v53, 0x3fb8aa3b, v53
	v_mul_f32_e32 v54, 0x3fb8aa3b, v54
	v_mul_f32_e32 v55, 0x3fb8aa3b, v55
	v_mul_f32_e32 v56, 0x3fb8aa3b, v56
	v_mul_f32_e32 v57, 0x3fb8aa3b, v57
	v_mul_f32_e32 v58, 0x3fb8aa3b, v58
	v_mul_f32_e32 v59, 0x3fb8aa3b, v59
	v_mul_f32_e32 v60, 0x3fb8aa3b, v60
	v_mul_f32_e32 v61, 0x3fb8aa3b, v61
	v_mul_f32_e32 v62, 0x3fb8aa3b, v62
	v_mul_f32_e32 v63, 0x3fb8aa3b, v63
	v_mul_f32_e32 v64, 0x3fb8aa3b, v64
	v_mul_f32_e32 v65, 0x3fb8aa3b, v65
	v_mul_f32_e32 v66, 0x3fb8aa3b, v66
	v_mul_f32_e32 v67, 0x3fb8aa3b, v67
	v_mul_f32_e32 v68, 0x3fb8aa3b, v68
	v_mul_f32_e32 v69, 0x3fb8aa3b, v69
	v_mul_f32_e32 v70, 0x3fb8aa3b, v70
	v_mul_f32_e32 v71, 0x3fb8aa3b, v71
	v_mul_f32_e32 v72, 0x3fb8aa3b, v72
	v_mul_f32_e32 v73, 0x3fb8aa3b, v73
	v_mul_f32_e32 v74, 0x3fb8aa3b, v74
	v_mul_f32_e32 v75, 0x3fb8aa3b, v75
	v_mul_f32_e32 v76, 0x3fb8aa3b, v76
	v_mul_f32_e32 v77, 0x3fb8aa3b, v77
	v_mul_f32_e32 v78, 0x3fb8aa3b, v78
	v_mul_f32_e32 v79, 0x3fb8aa3b, v79
	v_mul_f32_e32 v80, 0x3fb8aa3b, v80
	v_mul_f32_e32 v81, 0x3fb8aa3b, v81
	v_mul_f32_e32 v82, 0x3fb8aa3b, v82
	v_mul_f32_e32 v83, 0x3fb8aa3b, v83
	v_mul_f32_e32 v84, 0x3fb8aa3b, v84
	global_store_dword v13, v20, s[6:7]
	global_store_dword v13, v21, s[6:7] offset:256
	global_store_dword v13, v22, s[6:7] offset:512
	global_store_dword v13, v23, s[6:7] offset:768
	global_store_dword v13, v24, s[6:7] offset:1024
	global_store_dword v13, v25, s[6:7] offset:1280
	global_store_dword v13, v26, s[6:7] offset:1536
	global_store_dword v13, v27, s[6:7] offset:1792
	global_store_dword v13, v28, s[6:7] offset:2048
; DI void scan_unit(const Params& p, int su) {
;     ...
;         for (int i = 0; i < 65; ++i) { const int e = e0 + i; if (e < LP) { run += vals[i]; dst[e] = run * LOG2E; } else dst[e] = 0.f; }
;     } else {
;         const int sq = seq - 32, bb = sq >> 3, h = sq & 7;
;         const float* src0 = p.cbl + (size_t)bb * PAST * 8 + h;
;         const float* src1 = p.out + O_SBL + (size_t)bb * DSQ * 8 + h;
;         float* dst = p.c2s + (size_t)sq * LSK;
; #pragma unroll
;         for (int i = 0; i < 65; ++i) {
;             const int e = e0 + i, ec = e < LSK ? e : LSK - 1;
;             const float* pe = ec < PAST ? src0 + (size_t)ec * 8 : src1 + (size_t)(ec - PAST) * 8;
;             vals[i] = *pe;
;         }
	global_store_dword v13, v29, s[6:7] offset:2304
	global_store_dword v13, v30, s[6:7] offset:2560
	global_store_dword v13, v31, s[6:7] offset:2816
	global_store_dword v13, v32, s[6:7] offset:3072
	global_store_dword v13, v33, s[6:7] offset:3328
	global_store_dword v13, v34, s[6:7] offset:3584
	global_store_dword v13, v35, s[6:7] offset:3840
	s_add_u32 s6, s6, 0x1000
	s_addc_u32 s7, s7, 0
	global_store_dword v13, v36, s[6:7]
	global_store_dword v13, v37, s[6:7] offset:256
	global_store_dword v13, v38, s[6:7] offset:512
	global_store_dword v13, v39, s[6:7] offset:768
	global_store_dword v13, v40, s[6:7] offset:1024
	global_store_dword v13, v41, s[6:7] offset:1280
	global_store_dword v13, v42, s[6:7] offset:1536
	global_store_dword v13, v43, s[6:7] offset:1792
	global_store_dword v13, v44, s[6:7] offset:2048
	global_store_dword v13, v45, s[6:7] offset:2304
	global_store_dword v13, v46, s[6:7] offset:2560
	global_store_dword v13, v47, s[6:7] offset:2816
	global_store_dword v13, v48, s[6:7] offset:3072
	global_store_dword v13, v49, s[6:7] offset:3328
	global_store_dword v13, v50, s[6:7] offset:3584
	global_store_dword v13, v51, s[6:7] offset:3840
	s_add_u32 s6, s6, 0x1000
	s_addc_u32 s7, s7, 0
	global_store_dword v13, v52, s[6:7]
	global_store_dword v13, v53, s[6:7] offset:256
	global_store_dword v13, v54, s[6:7] offset:512
	global_store_dword v13, v55, s[6:7] offset:768
	global_store_dword v13, v56, s[6:7] offset:1024
	global_store_dword v13, v57, s[6:7] offset:1280
	global_store_dword v13, v58, s[6:7] offset:1536
	global_store_dword v13, v59, s[6:7] offset:1792
	global_store_dword v13, v60, s[6:7] offset:2048
	global_store_dword v13, v61, s[6:7] offset:2304
	global_store_dword v13, v62, s[6:7] offset:2560
	global_store_dword v13, v63, s[6:7] offset:2816
	global_store_dword v13, v64, s[6:7] offset:3072
	global_store_dword v13, v65, s[6:7] offset:3328
	global_store_dword v13, v66, s[6:7] offset:3584
	global_store_dword v13, v67, s[6:7] offset:3840
	s_add_u32 s6, s6, 0x1000
	s_addc_u32 s7, s7, 0
	global_store_dword v13, v68, s[6:7]
	global_store_dword v13, v69, s[6:7] offset:256
	global_store_dword v13, v70, s[6:7] offset:512
	global_store_dword v13, v71, s[6:7] offset:768
	global_store_dword v13, v72, s[6:7] offset:1024
	global_store_dword v13, v73, s[6:7] offset:1280
	global_store_dword v13, v74, s[6:7] offset:1536
	global_store_dword v13, v75, s[6:7] offset:1792
	global_store_dword v13, v76, s[6:7] offset:2048
	global_store_dword v13, v77, s[6:7] offset:2304
	global_store_dword v13, v78, s[6:7] offset:2560
	global_store_dword v13, v79, s[6:7] offset:2816
	global_store_dword v13, v80, s[6:7] offset:3072
	global_store_dword v13, v81, s[6:7] offset:3328
	global_store_dword v13, v82, s[6:7] offset:3584
	global_store_dword v13, v83, s[6:7] offset:3840
	s_add_u32 s6, s6, 0x1000
	s_addc_u32 s7, s7, 0
	v_cndmask_b32_e64 v84, 0, v84, s[4:5]
	global_store_dword v13, v84, s[6:7]
	s_branch .Lscn_done
.Lscn_smp:
	s_sub_i32 s0, s1, 32
	s_lshr_b32 s4, s0, 3
	s_and_b32 s5, s0, 7
	s_lshl_b32 s5, s5, 2
	s_lshl_b32 s6, s4, 10
	s_add_i32 s6, s6, s5
	s_add_i32 s6, s6, 0xc700800
	s_add_u32 vcc_lo, s54, s6
	s_addc_u32 vcc_hi, s55, 0
	s_lshl_b32 s4, s4, 17
	s_add_i32 s4, s4, s5
	s_add_u32 s4, s88, s4
	s_addc_u32 s5, s89, 0
	s_mul_i32 s6, s0, 0x4080
	s_add_u32 s6, s74, s6
	s_addc_u32 s7, s75, 0
	v_lshlrev_b32_e32 v11, 5, v10
	v_and_b32_e32 v12, 31, v10
	v_lshlrev_b32_e32 v12, 5, v12
	v_lshlrev_b32_e32 v13, 2, v10
	global_load_dword v20, v11, s[4:5]
	global_load_dword v21, v11, s[4:5] offset:2048
	s_add_u32 s4, s4, 0x1000
	s_addc_u32 s5, s5, 0
	global_load_dword v22, v11, s[4:5]
	global_load_dword v23, v11, s[4:5] offset:2048
	s_add_u32 s4, s4, 0x1000
	s_addc_u32 s5, s5, 0
	global_load_dword v24, v11, s[4:5]
	global_load_dword v25, v11, s[4:5] offset:2048
	s_add_u32 s4, s4, 0x1000
	s_addc_u32 s5, s5, 0
	global_load_dword v26, v11, s[4:5]
	global_load_dword v27, v11, s[4:5] offset:2048
	s_add_u32 s4, s4, 0x1000
	s_addc_u32 s5, s5, 0
	global_load_dword v28, v11, s[4:5]
	global_load_dword v29, v11, s[4:5] offset:2048
	s_add_u32 s4, s4, 0x1000
	s_addc_u32 s5, s5, 0
	global_load_dword v30, v11, s[4:5]
	global_load_dword v31, v11, s[4:5] offset:2048
	s_add_u32 s4, s4, 0x1000
	s_addc_u32 s5, s5, 0
	global_load_dword v32, v11, s[4:5]
	global_load_dword v33, v11, s[4:5] offset:2048
	s_add_u32 s4, s4, 0x1000
	s_addc_u32 s5, s5, 0
	global_load_dword v34, v11, s[4:5]
	global_load_dword v35, v11, s[4:5] offset:2048
	s_add_u32 s4, s4, 0x1000
	s_addc_u32 s5, s5, 0
	global_load_dword v36, v11, s[4:5]
	global_load_dword v37, v11, s[4:5] offset:2048
	s_add_u32 s4, s4, 0x1000
	s_addc_u32 s5, s5, 0
	global_load_dword v38, v11, s[4:5]
	global_load_dword v39, v11, s[4:5] offset:2048
	s_add_u32 s4, s4, 0x1000
	s_addc_u32 s5, s5, 0
	global_load_dword v40, v11, s[4:5]
	global_load_dword v41, v11, s[4:5] offset:2048
	s_add_u32 s4, s4, 0x1000
	s_addc_u32 s5, s5, 0
	global_load_dword v42, v11, s[4:5]
	global_load_dword v43, v11, s[4:5] offset:2048
	s_add_u32 s4, s4, 0x1000
	s_addc_u32 s5, s5, 0
	global_load_dword v44, v11, s[4:5]
	global_load_dword v45, v11, s[4:5] offset:2048
	s_add_u32 s4, s4, 0x1000
	s_addc_u32 s5, s5, 0
	global_load_dword v46, v11, s[4:5]
	global_load_dword v47, v11, s[4:5] offset:2048
	s_add_u32 s4, s4, 0x1000
	s_addc_u32 s5, s5, 0
	global_load_dword v48, v11, s[4:5]
	global_load_dword v49, v11, s[4:5] offset:2048
	s_add_u32 s4, s4, 0x1000
	s_addc_u32 s5, s5, 0
	global_load_dword v50, v11, s[4:5]
	global_load_dword v51, v11, s[4:5] offset:2048
	s_add_u32 s4, s4, 0x1000
	s_addc_u32 s5, s5, 0
	global_load_dword v52, v11, s[4:5]
	global_load_dword v53, v11, s[4:5] offset:2048
; DI void scan_unit(const Params& p, int su) {
;     ...
;         const int sq = seq - 32, bb = sq >> 3, h = sq & 7;
;         const float* src0 = p.cbl + (size_t)bb * PAST * 8 + h;
;         const float* src1 = p.out + O_SBL + (size_t)bb * DSQ * 8 + h;
;         float* dst = p.c2s + (size_t)sq * LSK;
; #pragma unroll
;         for (int i = 0; i < 65; ++i) {
;             const int e = e0 + i, ec = e < LSK ? e : LSK - 1;
;             const float* pe = ec < PAST ? src0 + (size_t)ec * 8 : src1 + (size_t)(ec - PAST) * 8;
;             vals[i] = *pe;
;         }
;         float s = 0.f;
; #pragma unroll
;         for (int i = 0; i < 65; ++i) s += (e0 + i < LSK) ? vals[i] : 0.f;
;         float incl = s;
; #pragma unroll
;         for (int o = 1; o < 64; o <<= 1) { const float t = __shfl_up(incl, o); if (lane >= o) incl += t; }
	s_add_u32 s4, s4, 0x1000
	s_addc_u32 s5, s5, 0
	global_load_dword v54, v11, s[4:5]
	global_load_dword v55, v11, s[4:5] offset:2048
	s_add_u32 s4, s4, 0x1000
	s_addc_u32 s5, s5, 0
	global_load_dword v56, v11, s[4:5]
	global_load_dword v57, v11, s[4:5] offset:2048
	s_add_u32 s4, s4, 0x1000
	s_addc_u32 s5, s5, 0
	global_load_dword v58, v11, s[4:5]
	global_load_dword v59, v11, s[4:5] offset:2048
	s_add_u32 s4, s4, 0x1000
	s_addc_u32 s5, s5, 0
	global_load_dword v60, v11, s[4:5]
	global_load_dword v61, v11, s[4:5] offset:2048
	s_add_u32 s4, s4, 0x1000
	s_addc_u32 s5, s5, 0
	global_load_dword v62, v11, s[4:5]
	global_load_dword v63, v11, s[4:5] offset:2048
	s_add_u32 s4, s4, 0x1000
	s_addc_u32 s5, s5, 0
	global_load_dword v64, v11, s[4:5]
	global_load_dword v65, v11, s[4:5] offset:2048
	s_add_u32 s4, s4, 0x1000
	s_addc_u32 s5, s5, 0
	global_load_dword v66, v11, s[4:5]
	global_load_dword v67, v11, s[4:5] offset:2048
	s_add_u32 s4, s4, 0x1000
	s_addc_u32 s5, s5, 0
	global_load_dword v68, v11, s[4:5]
	global_load_dword v69, v11, s[4:5] offset:2048
	s_add_u32 s4, s4, 0x1000
	s_addc_u32 s5, s5, 0
	global_load_dword v70, v11, s[4:5]
	global_load_dword v71, v11, s[4:5] offset:2048
	s_add_u32 s4, s4, 0x1000
	s_addc_u32 s5, s5, 0
	global_load_dword v72, v11, s[4:5]
	global_load_dword v73, v11, s[4:5] offset:2048
	s_add_u32 s4, s4, 0x1000
	s_addc_u32 s5, s5, 0
	global_load_dword v74, v11, s[4:5]
	global_load_dword v75, v11, s[4:5] offset:2048
	s_add_u32 s4, s4, 0x1000
	s_addc_u32 s5, s5, 0
	global_load_dword v76, v11, s[4:5]
	global_load_dword v77, v11, s[4:5] offset:2048
	s_add_u32 s4, s4, 0x1000
	s_addc_u32 s5, s5, 0
	global_load_dword v78, v11, s[4:5]
	global_load_dword v79, v11, s[4:5] offset:2048
	s_add_u32 s4, s4, 0x1000
	s_addc_u32 s5, s5, 0
	global_load_dword v80, v11, s[4:5]
	global_load_dword v81, v11, s[4:5] offset:2048
	s_add_u32 s4, s4, 0x1000
	s_addc_u32 s5, s5, 0
	global_load_dword v82, v11, s[4:5]
	global_load_dword v83, v11, s[4:5] offset:2048
	s_add_u32 s4, s4, 0x1000
	s_addc_u32 s5, s5, 0
	global_load_dword v84, v12, vcc
	v_cmp_gt_u32_e64 s[4:5], 32, v10
	s_waitcnt vmcnt(0)
	v_cndmask_b32_e64 v84, 0, v84, s[4:5]
	v_add_f32_dpp v20, v20, v20 row_shr:1 row_mask:0xf bank_mask:0xf
	v_add_f32_dpp v21, v21, v21 row_shr:1 row_mask:0xf bank_mask:0xf
	v_add_f32_dpp v22, v22, v22 row_shr:1 row_mask:0xf bank_mask:0xf
	v_add_f32_dpp v23, v23, v23 row_shr:1 row_mask:0xf bank_mask:0xf
	v_add_f32_dpp v20, v20, v20 row_shr:2 row_mask:0xf bank_mask:0xf
	v_add_f32_dpp v21, v21, v21 row_shr:2 row_mask:0xf bank_mask:0xf
	v_add_f32_dpp v22, v22, v22 row_shr:2 row_mask:0xf bank_mask:0xf
	v_add_f32_dpp v23, v23, v23 row_shr:2 row_mask:0xf bank_mask:0xf
	v_add_f32_dpp v20, v20, v20 row_shr:4 row_mask:0xf bank_mask:0xf
	v_add_f32_dpp v21, v21, v21 row_shr:4 row_mask:0xf bank_mask:0xf
	v_add_f32_dpp v22, v22, v22 row_shr:4 row_mask:0xf bank_mask:0xf
	v_add_f32_dpp v23, v23, v23 row_shr:4 row_mask:0xf bank_mask:0xf
	v_add_f32_dpp v20, v20, v20 row_shr:8 row_mask:0xf bank_mask:0xf
	v_add_f32_dpp v21, v21, v21 row_shr:8 row_mask:0xf bank_mask:0xf
	v_add_f32_dpp v22, v22, v22 row_shr:8 row_mask:0xf bank_mask:0xf
	v_add_f32_dpp v23, v23, v23 row_shr:8 row_mask:0xf bank_mask:0xf
	v_add_f32_dpp v20, v20, v20 row_bcast:15 row_mask:0xa bank_mask:0xf
	v_add_f32_dpp v21, v21, v21 row_bcast:15 row_mask:0xa bank_mask:0xf
	v_add_f32_dpp v22, v22, v22 row_bcast:15 row_mask:0xa bank_mask:0xf
	v_add_f32_dpp v23, v23, v23 row_bcast:15 row_mask:0xa bank_mask:0xf
	v_add_f32_dpp v20, v20, v20 row_bcast:31 row_mask:0xc bank_mask:0xf
	v_add_f32_dpp v21, v21, v21 row_bcast:31 row_mask:0xc bank_mask:0xf
	v_add_f32_dpp v22, v22, v22 row_bcast:31 row_mask:0xc bank_mask:0xf
	v_add_f32_dpp v23, v23, v23 row_bcast:31 row_mask:0xc bank_mask:0xf
	v_add_f32_dpp v24, v24, v24 row_shr:1 row_mask:0xf bank_mask:0xf
	v_add_f32_dpp v25, v25, v25 row_shr:1 row_mask:0xf bank_mask:0xf
	v_add_f32_dpp v26, v26, v26 row_shr:1 row_mask:0xf bank_mask:0xf
	v_add_f32_dpp v27, v27, v27 row_shr:1 row_mask:0xf bank_mask:0xf
	v_add_f32_dpp v24, v24, v24 row_shr:2 row_mask:0xf bank_mask:0xf
	v_add_f32_dpp v25, v25, v25 row_shr:2 row_mask:0xf bank_mask:0xf
	v_add_f32_dpp v26, v26, v26 row_shr:2 row_mask:0xf bank_mask:0xf
	v_add_f32_dpp v27, v27, v27 row_shr:2 row_mask:0xf bank_mask:0xf
	v_add_f32_dpp v24, v24, v24 row_shr:4 row_mask:0xf bank_mask:0xf
	v_add_f32_dpp v25, v25, v25 row_shr:4 row_mask:0xf bank_mask:0xf
	v_add_f32_dpp v26, v26, v26 row_shr:4 row_mask:0xf bank_mask:0xf
	v_add_f32_dpp v27, v27, v27 row_shr:4 row_mask:0xf bank_mask:0xf
	v_add_f32_dpp v24, v24, v24 row_shr:8 row_mask:0xf bank_mask:0xf
	v_add_f32_dpp v25, v25, v25 row_shr:8 row_mask:0xf bank_mask:0xf
	v_add_f32_dpp v26, v26, v26 row_shr:8 row_mask:0xf bank_mask:0xf
	v_add_f32_dpp v27, v27, v27 row_shr:8 row_mask:0xf bank_mask:0xf
	v_add_f32_dpp v24, v24, v24 row_bcast:15 row_mask:0xa bank_mask:0xf
	v_add_f32_dpp v25, v25, v25 row_bcast:15 row_mask:0xa bank_mask:0xf
	v_add_f32_dpp v26, v26, v26 row_bcast:15 row_mask:0xa bank_mask:0xf
	v_add_f32_dpp v27, v27, v27 row_bcast:15 row_mask:0xa bank_mask:0xf
	v_add_f32_dpp v24, v24, v24 row_bcast:31 row_mask:0xc bank_mask:0xf
	v_add_f32_dpp v25, v25, v25 row_bcast:31 row_mask:0xc bank_mask:0xf
	v_add_f32_dpp v26, v26, v26 row_bcast:31 row_mask:0xc bank_mask:0xf
	v_add_f32_dpp v27, v27, v27 row_bcast:31 row_mask:0xc bank_mask:0xf
	v_add_f32_dpp v28, v28, v28 row_shr:1 row_mask:0xf bank_mask:0xf
	v_add_f32_dpp v29, v29, v29 row_shr:1 row_mask:0xf bank_mask:0xf
	v_add_f32_dpp v30, v30, v30 row_shr:1 row_mask:0xf bank_mask:0xf
	v_add_f32_dpp v31, v31, v31 row_shr:1 row_mask:0xf bank_mask:0xf
; DI void scan_unit(const Params& p, int su) {
;     ...
; #pragma unroll
;         for (int i = 0; i < 65; ++i) s += (e0 + i < LSK) ? vals[i] : 0.f;
;         float incl = s;
; #pragma unroll
;         for (int o = 1; o < 64; o <<= 1) { const float t = __shfl_up(incl, o); if (lane >= o) incl += t; }
	v_add_f32_dpp v28, v28, v28 row_shr:2 row_mask:0xf bank_mask:0xf
	v_add_f32_dpp v29, v29, v29 row_shr:2 row_mask:0xf bank_mask:0xf
	v_add_f32_dpp v30, v30, v30 row_shr:2 row_mask:0xf bank_mask:0xf
	v_add_f32_dpp v31, v31, v31 row_shr:2 row_mask:0xf bank_mask:0xf
	v_add_f32_dpp v28, v28, v28 row_shr:4 row_mask:0xf bank_mask:0xf
	v_add_f32_dpp v29, v29, v29 row_shr:4 row_mask:0xf bank_mask:0xf
	v_add_f32_dpp v30, v30, v30 row_shr:4 row_mask:0xf bank_mask:0xf
	v_add_f32_dpp v31, v31, v31 row_shr:4 row_mask:0xf bank_mask:0xf
	v_add_f32_dpp v28, v28, v28 row_shr:8 row_mask:0xf bank_mask:0xf
	v_add_f32_dpp v29, v29, v29 row_shr:8 row_mask:0xf bank_mask:0xf
	v_add_f32_dpp v30, v30, v30 row_shr:8 row_mask:0xf bank_mask:0xf
	v_add_f32_dpp v31, v31, v31 row_shr:8 row_mask:0xf bank_mask:0xf
	v_add_f32_dpp v28, v28, v28 row_bcast:15 row_mask:0xa bank_mask:0xf
	v_add_f32_dpp v29, v29, v29 row_bcast:15 row_mask:0xa bank_mask:0xf
	v_add_f32_dpp v30, v30, v30 row_bcast:15 row_mask:0xa bank_mask:0xf
	v_add_f32_dpp v31, v31, v31 row_bcast:15 row_mask:0xa bank_mask:0xf
	v_add_f32_dpp v28, v28, v28 row_bcast:31 row_mask:0xc bank_mask:0xf
	v_add_f32_dpp v29, v29, v29 row_bcast:31 row_mask:0xc bank_mask:0xf
	v_add_f32_dpp v30, v30, v30 row_bcast:31 row_mask:0xc bank_mask:0xf
	v_add_f32_dpp v31, v31, v31 row_bcast:31 row_mask:0xc bank_mask:0xf
	v_add_f32_dpp v32, v32, v32 row_shr:1 row_mask:0xf bank_mask:0xf
	v_add_f32_dpp v33, v33, v33 row_shr:1 row_mask:0xf bank_mask:0xf
	v_add_f32_dpp v34, v34, v34 row_shr:1 row_mask:0xf bank_mask:0xf
	v_add_f32_dpp v35, v35, v35 row_shr:1 row_mask:0xf bank_mask:0xf
	v_add_f32_dpp v32, v32, v32 row_shr:2 row_mask:0xf bank_mask:0xf
	v_add_f32_dpp v33, v33, v33 row_shr:2 row_mask:0xf bank_mask:0xf
	v_add_f32_dpp v34, v34, v34 row_shr:2 row_mask:0xf bank_mask:0xf
	v_add_f32_dpp v35, v35, v35 row_shr:2 row_mask:0xf bank_mask:0xf
	v_add_f32_dpp v32, v32, v32 row_shr:4 row_mask:0xf bank_mask:0xf
	v_add_f32_dpp v33, v33, v33 row_shr:4 row_mask:0xf bank_mask:0xf
	v_add_f32_dpp v34, v34, v34 row_shr:4 row_mask:0xf bank_mask:0xf
	v_add_f32_dpp v35, v35, v35 row_shr:4 row_mask:0xf bank_mask:0xf
	v_add_f32_dpp v32, v32, v32 row_shr:8 row_mask:0xf bank_mask:0xf
	v_add_f32_dpp v33, v33, v33 row_shr:8 row_mask:0xf bank_mask:0xf
	v_add_f32_dpp v34, v34, v34 row_shr:8 row_mask:0xf bank_mask:0xf
	v_add_f32_dpp v35, v35, v35 row_shr:8 row_mask:0xf bank_mask:0xf
	v_add_f32_dpp v32, v32, v32 row_bcast:15 row_mask:0xa bank_mask:0xf
	v_add_f32_dpp v33, v33, v33 row_bcast:15 row_mask:0xa bank_mask:0xf
	v_add_f32_dpp v34, v34, v34 row_bcast:15 row_mask:0xa bank_mask:0xf
	v_add_f32_dpp v35, v35, v35 row_bcast:15 row_mask:0xa bank_mask:0xf
	v_add_f32_dpp v32, v32, v32 row_bcast:31 row_mask:0xc bank_mask:0xf
	v_add_f32_dpp v33, v33, v33 row_bcast:31 row_mask:0xc bank_mask:0xf
	v_add_f32_dpp v34, v34, v34 row_bcast:31 row_mask:0xc bank_mask:0xf
	v_add_f32_dpp v35, v35, v35 row_bcast:31 row_mask:0xc bank_mask:0xf
	v_add_f32_dpp v36, v36, v36 row_shr:1 row_mask:0xf bank_mask:0xf
	v_add_f32_dpp v37, v37, v37 row_shr:1 row_mask:0xf bank_mask:0xf
	v_add_f32_dpp v38, v38, v38 row_shr:1 row_mask:0xf bank_mask:0xf
	v_add_f32_dpp v39, v39, v39 row_shr:1 row_mask:0xf bank_mask:0xf
	v_add_f32_dpp v36, v36, v36 row_shr:2 row_mask:0xf bank_mask:0xf
	v_add_f32_dpp v37, v37, v37 row_shr:2 row_mask:0xf bank_mask:0xf
	v_add_f32_dpp v38, v38, v38 row_shr:2 row_mask:0xf bank_mask:0xf
	v_add_f32_dpp v39, v39, v39 row_shr:2 row_mask:0xf bank_mask:0xf
	v_add_f32_dpp v36, v36, v36 row_shr:4 row_mask:0xf bank_mask:0xf
	v_add_f32_dpp v37, v37, v37 row_shr:4 row_mask:0xf bank_mask:0xf
	v_add_f32_dpp v38, v38, v38 row_shr:4 row_mask:0xf bank_mask:0xf
	v_add_f32_dpp v39, v39, v39 row_shr:4 row_mask:0xf bank_mask:0xf
	v_add_f32_dpp v36, v36, v36 row_shr:8 row_mask:0xf bank_mask:0xf
	v_add_f32_dpp v37, v37, v37 row_shr:8 row_mask:0xf bank_mask:0xf
	v_add_f32_dpp v38, v38, v38 row_shr:8 row_mask:0xf bank_mask:0xf
	v_add_f32_dpp v39, v39, v39 row_shr:8 row_mask:0xf bank_mask:0xf
	v_add_f32_dpp v36, v36, v36 row_bcast:15 row_mask:0xa bank_mask:0xf
	v_add_f32_dpp v37, v37, v37 row_bcast:15 row_mask:0xa bank_mask:0xf
	v_add_f32_dpp v38, v38, v38 row_bcast:15 row_mask:0xa bank_mask:0xf
	v_add_f32_dpp v39, v39, v39 row_bcast:15 row_mask:0xa bank_mask:0xf
	v_add_f32_dpp v36, v36, v36 row_bcast:31 row_mask:0xc bank_mask:0xf
	v_add_f32_dpp v37, v37, v37 row_bcast:31 row_mask:0xc bank_mask:0xf
	v_add_f32_dpp v38, v38, v38 row_bcast:31 row_mask:0xc bank_mask:0xf
	v_add_f32_dpp v39, v39, v39 row_bcast:31 row_mask:0xc bank_mask:0xf
	v_add_f32_dpp v40, v40, v40 row_shr:1 row_mask:0xf bank_mask:0xf
	v_add_f32_dpp v41, v41, v41 row_shr:1 row_mask:0xf bank_mask:0xf
	v_add_f32_dpp v42, v42, v42 row_shr:1 row_mask:0xf bank_mask:0xf
	v_add_f32_dpp v43, v43, v43 row_shr:1 row_mask:0xf bank_mask:0xf
	v_add_f32_dpp v40, v40, v40 row_shr:2 row_mask:0xf bank_mask:0xf
	v_add_f32_dpp v41, v41, v41 row_shr:2 row_mask:0xf bank_mask:0xf
	v_add_f32_dpp v42, v42, v42 row_shr:2 row_mask:0xf bank_mask:0xf
	v_add_f32_dpp v43, v43, v43 row_shr:2 row_mask:0xf bank_mask:0xf
	v_add_f32_dpp v40, v40, v40 row_shr:4 row_mask:0xf bank_mask:0xf
	v_add_f32_dpp v41, v41, v41 row_shr:4 row_mask:0xf bank_mask:0xf
	v_add_f32_dpp v42, v42, v42 row_shr:4 row_mask:0xf bank_mask:0xf
	v_add_f32_dpp v43, v43, v43 row_shr:4 row_mask:0xf bank_mask:0xf
	v_add_f32_dpp v40, v40, v40 row_shr:8 row_mask:0xf bank_mask:0xf
	v_add_f32_dpp v41, v41, v41 row_shr:8 row_mask:0xf bank_mask:0xf
	v_add_f32_dpp v42, v42, v42 row_shr:8 row_mask:0xf bank_mask:0xf
	v_add_f32_dpp v43, v43, v43 row_shr:8 row_mask:0xf bank_mask:0xf
; DI void scan_unit(const Params& p, int su) {
;     ...
; #pragma unroll
;         for (int i = 0; i < 65; ++i) s += (e0 + i < LSK) ? vals[i] : 0.f;
;         float incl = s;
; #pragma unroll
;         for (int o = 1; o < 64; o <<= 1) { const float t = __shfl_up(incl, o); if (lane >= o) incl += t; }
	v_add_f32_dpp v40, v40, v40 row_bcast:15 row_mask:0xa bank_mask:0xf
	v_add_f32_dpp v41, v41, v41 row_bcast:15 row_mask:0xa bank_mask:0xf
	v_add_f32_dpp v42, v42, v42 row_bcast:15 row_mask:0xa bank_mask:0xf
	v_add_f32_dpp v43, v43, v43 row_bcast:15 row_mask:0xa bank_mask:0xf
	v_add_f32_dpp v40, v40, v40 row_bcast:31 row_mask:0xc bank_mask:0xf
	v_add_f32_dpp v41, v41, v41 row_bcast:31 row_mask:0xc bank_mask:0xf
	v_add_f32_dpp v42, v42, v42 row_bcast:31 row_mask:0xc bank_mask:0xf
	v_add_f32_dpp v43, v43, v43 row_bcast:31 row_mask:0xc bank_mask:0xf
	v_add_f32_dpp v44, v44, v44 row_shr:1 row_mask:0xf bank_mask:0xf
	v_add_f32_dpp v45, v45, v45 row_shr:1 row_mask:0xf bank_mask:0xf
	v_add_f32_dpp v46, v46, v46 row_shr:1 row_mask:0xf bank_mask:0xf
	v_add_f32_dpp v47, v47, v47 row_shr:1 row_mask:0xf bank_mask:0xf
	v_add_f32_dpp v44, v44, v44 row_shr:2 row_mask:0xf bank_mask:0xf
	v_add_f32_dpp v45, v45, v45 row_shr:2 row_mask:0xf bank_mask:0xf
	v_add_f32_dpp v46, v46, v46 row_shr:2 row_mask:0xf bank_mask:0xf
	v_add_f32_dpp v47, v47, v47 row_shr:2 row_mask:0xf bank_mask:0xf
	v_add_f32_dpp v44, v44, v44 row_shr:4 row_mask:0xf bank_mask:0xf
	v_add_f32_dpp v45, v45, v45 row_shr:4 row_mask:0xf bank_mask:0xf
	v_add_f32_dpp v46, v46, v46 row_shr:4 row_mask:0xf bank_mask:0xf
	v_add_f32_dpp v47, v47, v47 row_shr:4 row_mask:0xf bank_mask:0xf
	v_add_f32_dpp v44, v44, v44 row_shr:8 row_mask:0xf bank_mask:0xf
	v_add_f32_dpp v45, v45, v45 row_shr:8 row_mask:0xf bank_mask:0xf
	v_add_f32_dpp v46, v46, v46 row_shr:8 row_mask:0xf bank_mask:0xf
	v_add_f32_dpp v47, v47, v47 row_shr:8 row_mask:0xf bank_mask:0xf
	v_add_f32_dpp v44, v44, v44 row_bcast:15 row_mask:0xa bank_mask:0xf
	v_add_f32_dpp v45, v45, v45 row_bcast:15 row_mask:0xa bank_mask:0xf
	v_add_f32_dpp v46, v46, v46 row_bcast:15 row_mask:0xa bank_mask:0xf
	v_add_f32_dpp v47, v47, v47 row_bcast:15 row_mask:0xa bank_mask:0xf
	v_add_f32_dpp v44, v44, v44 row_bcast:31 row_mask:0xc bank_mask:0xf
	v_add_f32_dpp v45, v45, v45 row_bcast:31 row_mask:0xc bank_mask:0xf
	v_add_f32_dpp v46, v46, v46 row_bcast:31 row_mask:0xc bank_mask:0xf
	v_add_f32_dpp v47, v47, v47 row_bcast:31 row_mask:0xc bank_mask:0xf
	v_add_f32_dpp v48, v48, v48 row_shr:1 row_mask:0xf bank_mask:0xf
	v_add_f32_dpp v49, v49, v49 row_shr:1 row_mask:0xf bank_mask:0xf
	v_add_f32_dpp v50, v50, v50 row_shr:1 row_mask:0xf bank_mask:0xf
	v_add_f32_dpp v51, v51, v51 row_shr:1 row_mask:0xf bank_mask:0xf
	v_add_f32_dpp v48, v48, v48 row_shr:2 row_mask:0xf bank_mask:0xf
	v_add_f32_dpp v49, v49, v49 row_shr:2 row_mask:0xf bank_mask:0xf
	v_add_f32_dpp v50, v50, v50 row_shr:2 row_mask:0xf bank_mask:0xf
	v_add_f32_dpp v51, v51, v51 row_shr:2 row_mask:0xf bank_mask:0xf
	v_add_f32_dpp v48, v48, v48 row_shr:4 row_mask:0xf bank_mask:0xf
	v_add_f32_dpp v49, v49, v49 row_shr:4 row_mask:0xf bank_mask:0xf
	v_add_f32_dpp v50, v50, v50 row_shr:4 row_mask:0xf bank_mask:0xf
	v_add_f32_dpp v51, v51, v51 row_shr:4 row_mask:0xf bank_mask:0xf
	v_add_f32_dpp v48, v48, v48 row_shr:8 row_mask:0xf bank_mask:0xf
	v_add_f32_dpp v49, v49, v49 row_shr:8 row_mask:0xf bank_mask:0xf
	v_add_f32_dpp v50, v50, v50 row_shr:8 row_mask:0xf bank_mask:0xf
	v_add_f32_dpp v51, v51, v51 row_shr:8 row_mask:0xf bank_mask:0xf
	v_add_f32_dpp v48, v48, v48 row_bcast:15 row_mask:0xa bank_mask:0xf
	v_add_f32_dpp v49, v49, v49 row_bcast:15 row_mask:0xa bank_mask:0xf
	v_add_f32_dpp v50, v50, v50 row_bcast:15 row_mask:0xa bank_mask:0xf
	v_add_f32_dpp v51, v51, v51 row_bcast:15 row_mask:0xa bank_mask:0xf
	v_add_f32_dpp v48, v48, v48 row_bcast:31 row_mask:0xc bank_mask:0xf
	v_add_f32_dpp v49, v49, v49 row_bcast:31 row_mask:0xc bank_mask:0xf
	v_add_f32_dpp v50, v50, v50 row_bcast:31 row_mask:0xc bank_mask:0xf
	v_add_f32_dpp v51, v51, v51 row_bcast:31 row_mask:0xc bank_mask:0xf
	v_add_f32_dpp v52, v52, v52 row_shr:1 row_mask:0xf bank_mask:0xf
	v_add_f32_dpp v53, v53, v53 row_shr:1 row_mask:0xf bank_mask:0xf
	v_add_f32_dpp v54, v54, v54 row_shr:1 row_mask:0xf bank_mask:0xf
	v_add_f32_dpp v55, v55, v55 row_shr:1 row_mask:0xf bank_mask:0xf
	v_add_f32_dpp v52, v52, v52 row_shr:2 row_mask:0xf bank_mask:0xf
	v_add_f32_dpp v53, v53, v53 row_shr:2 row_mask:0xf bank_mask:0xf
	v_add_f32_dpp v54, v54, v54 row_shr:2 row_mask:0xf bank_mask:0xf
	v_add_f32_dpp v55, v55, v55 row_shr:2 row_mask:0xf bank_mask:0xf
	v_add_f32_dpp v52, v52, v52 row_shr:4 row_mask:0xf bank_mask:0xf
	v_add_f32_dpp v53, v53, v53 row_shr:4 row_mask:0xf bank_mask:0xf
	v_add_f32_dpp v54, v54, v54 row_shr:4 row_mask:0xf bank_mask:0xf
	v_add_f32_dpp v55, v55, v55 row_shr:4 row_mask:0xf bank_mask:0xf
	v_add_f32_dpp v52, v52, v52 row_shr:8 row_mask:0xf bank_mask:0xf
	v_add_f32_dpp v53, v53, v53 row_shr:8 row_mask:0xf bank_mask:0xf
	v_add_f32_dpp v54, v54, v54 row_shr:8 row_mask:0xf bank_mask:0xf
	v_add_f32_dpp v55, v55, v55 row_shr:8 row_mask:0xf bank_mask:0xf
	v_add_f32_dpp v52, v52, v52 row_bcast:15 row_mask:0xa bank_mask:0xf
	v_add_f32_dpp v53, v53, v53 row_bcast:15 row_mask:0xa bank_mask:0xf
	v_add_f32_dpp v54, v54, v54 row_bcast:15 row_mask:0xa bank_mask:0xf
	v_add_f32_dpp v55, v55, v55 row_bcast:15 row_mask:0xa bank_mask:0xf
	v_add_f32_dpp v52, v52, v52 row_bcast:31 row_mask:0xc bank_mask:0xf
	v_add_f32_dpp v53, v53, v53 row_bcast:31 row_mask:0xc bank_mask:0xf
	v_add_f32_dpp v54, v54, v54 row_bcast:31 row_mask:0xc bank_mask:0xf
	v_add_f32_dpp v55, v55, v55 row_bcast:31 row_mask:0xc bank_mask:0xf
	v_add_f32_dpp v56, v56, v56 row_shr:1 row_mask:0xf bank_mask:0xf
	v_add_f32_dpp v57, v57, v57 row_shr:1 row_mask:0xf bank_mask:0xf
	v_add_f32_dpp v58, v58, v58 row_shr:1 row_mask:0xf bank_mask:0xf
	v_add_f32_dpp v59, v59, v59 row_shr:1 row_mask:0xf bank_mask:0xf
; DI void scan_unit(const Params& p, int su) {
;     ...
; #pragma unroll
;         for (int i = 0; i < 65; ++i) s += (e0 + i < LSK) ? vals[i] : 0.f;
;         float incl = s;
; #pragma unroll
;         for (int o = 1; o < 64; o <<= 1) { const float t = __shfl_up(incl, o); if (lane >= o) incl += t; }
	v_add_f32_dpp v56, v56, v56 row_shr:2 row_mask:0xf bank_mask:0xf
	v_add_f32_dpp v57, v57, v57 row_shr:2 row_mask:0xf bank_mask:0xf
	v_add_f32_dpp v58, v58, v58 row_shr:2 row_mask:0xf bank_mask:0xf
	v_add_f32_dpp v59, v59, v59 row_shr:2 row_mask:0xf bank_mask:0xf
	v_add_f32_dpp v56, v56, v56 row_shr:4 row_mask:0xf bank_mask:0xf
	v_add_f32_dpp v57, v57, v57 row_shr:4 row_mask:0xf bank_mask:0xf
	v_add_f32_dpp v58, v58, v58 row_shr:4 row_mask:0xf bank_mask:0xf
	v_add_f32_dpp v59, v59, v59 row_shr:4 row_mask:0xf bank_mask:0xf
	v_add_f32_dpp v56, v56, v56 row_shr:8 row_mask:0xf bank_mask:0xf
	v_add_f32_dpp v57, v57, v57 row_shr:8 row_mask:0xf bank_mask:0xf
	v_add_f32_dpp v58, v58, v58 row_shr:8 row_mask:0xf bank_mask:0xf
	v_add_f32_dpp v59, v59, v59 row_shr:8 row_mask:0xf bank_mask:0xf
	v_add_f32_dpp v56, v56, v56 row_bcast:15 row_mask:0xa bank_mask:0xf
	v_add_f32_dpp v57, v57, v57 row_bcast:15 row_mask:0xa bank_mask:0xf
	v_add_f32_dpp v58, v58, v58 row_bcast:15 row_mask:0xa bank_mask:0xf
	v_add_f32_dpp v59, v59, v59 row_bcast:15 row_mask:0xa bank_mask:0xf
	v_add_f32_dpp v56, v56, v56 row_bcast:31 row_mask:0xc bank_mask:0xf
	v_add_f32_dpp v57, v57, v57 row_bcast:31 row_mask:0xc bank_mask:0xf
	v_add_f32_dpp v58, v58, v58 row_bcast:31 row_mask:0xc bank_mask:0xf
	v_add_f32_dpp v59, v59, v59 row_bcast:31 row_mask:0xc bank_mask:0xf
	v_add_f32_dpp v60, v60, v60 row_shr:1 row_mask:0xf bank_mask:0xf
	v_add_f32_dpp v61, v61, v61 row_shr:1 row_mask:0xf bank_mask:0xf
	v_add_f32_dpp v62, v62, v62 row_shr:1 row_mask:0xf bank_mask:0xf
	v_add_f32_dpp v63, v63, v63 row_shr:1 row_mask:0xf bank_mask:0xf
	v_add_f32_dpp v60, v60, v60 row_shr:2 row_mask:0xf bank_mask:0xf
	v_add_f32_dpp v61, v61, v61 row_shr:2 row_mask:0xf bank_mask:0xf
	v_add_f32_dpp v62, v62, v62 row_shr:2 row_mask:0xf bank_mask:0xf
	v_add_f32_dpp v63, v63, v63 row_shr:2 row_mask:0xf bank_mask:0xf
	v_add_f32_dpp v60, v60, v60 row_shr:4 row_mask:0xf bank_mask:0xf
	v_add_f32_dpp v61, v61, v61 row_shr:4 row_mask:0xf bank_mask:0xf
	v_add_f32_dpp v62, v62, v62 row_shr:4 row_mask:0xf bank_mask:0xf
	v_add_f32_dpp v63, v63, v63 row_shr:4 row_mask:0xf bank_mask:0xf
	v_add_f32_dpp v60, v60, v60 row_shr:8 row_mask:0xf bank_mask:0xf
	v_add_f32_dpp v61, v61, v61 row_shr:8 row_mask:0xf bank_mask:0xf
	v_add_f32_dpp v62, v62, v62 row_shr:8 row_mask:0xf bank_mask:0xf
	v_add_f32_dpp v63, v63, v63 row_shr:8 row_mask:0xf bank_mask:0xf
	v_add_f32_dpp v60, v60, v60 row_bcast:15 row_mask:0xa bank_mask:0xf
	v_add_f32_dpp v61, v61, v61 row_bcast:15 row_mask:0xa bank_mask:0xf
	v_add_f32_dpp v62, v62, v62 row_bcast:15 row_mask:0xa bank_mask:0xf
	v_add_f32_dpp v63, v63, v63 row_bcast:15 row_mask:0xa bank_mask:0xf
	v_add_f32_dpp v60, v60, v60 row_bcast:31 row_mask:0xc bank_mask:0xf
	v_add_f32_dpp v61, v61, v61 row_bcast:31 row_mask:0xc bank_mask:0xf
	v_add_f32_dpp v62, v62, v62 row_bcast:31 row_mask:0xc bank_mask:0xf
	v_add_f32_dpp v63, v63, v63 row_bcast:31 row_mask:0xc bank_mask:0xf
	v_add_f32_dpp v64, v64, v64 row_shr:1 row_mask:0xf bank_mask:0xf
	v_add_f32_dpp v65, v65, v65 row_shr:1 row_mask:0xf bank_mask:0xf
	v_add_f32_dpp v66, v66, v66 row_shr:1 row_mask:0xf bank_mask:0xf
	v_add_f32_dpp v67, v67, v67 row_shr:1 row_mask:0xf bank_mask:0xf
	v_add_f32_dpp v64, v64, v64 row_shr:2 row_mask:0xf bank_mask:0xf
	v_add_f32_dpp v65, v65, v65 row_shr:2 row_mask:0xf bank_mask:0xf
	v_add_f32_dpp v66, v66, v66 row_shr:2 row_mask:0xf bank_mask:0xf
	v_add_f32_dpp v67, v67, v67 row_shr:2 row_mask:0xf bank_mask:0xf
	v_add_f32_dpp v64, v64, v64 row_shr:4 row_mask:0xf bank_mask:0xf
	v_add_f32_dpp v65, v65, v65 row_shr:4 row_mask:0xf bank_mask:0xf
	v_add_f32_dpp v66, v66, v66 row_shr:4 row_mask:0xf bank_mask:0xf
	v_add_f32_dpp v67, v67, v67 row_shr:4 row_mask:0xf bank_mask:0xf
	v_add_f32_dpp v64, v64, v64 row_shr:8 row_mask:0xf bank_mask:0xf
	v_add_f32_dpp v65, v65, v65 row_shr:8 row_mask:0xf bank_mask:0xf
	v_add_f32_dpp v66, v66, v66 row_shr:8 row_mask:0xf bank_mask:0xf
	v_add_f32_dpp v67, v67, v67 row_shr:8 row_mask:0xf bank_mask:0xf
	v_add_f32_dpp v64, v64, v64 row_bcast:15 row_mask:0xa bank_mask:0xf
	v_add_f32_dpp v65, v65, v65 row_bcast:15 row_mask:0xa bank_mask:0xf
	v_add_f32_dpp v66, v66, v66 row_bcast:15 row_mask:0xa bank_mask:0xf
	v_add_f32_dpp v67, v67, v67 row_bcast:15 row_mask:0xa bank_mask:0xf
	v_add_f32_dpp v64, v64, v64 row_bcast:31 row_mask:0xc bank_mask:0xf
	v_add_f32_dpp v65, v65, v65 row_bcast:31 row_mask:0xc bank_mask:0xf
	v_add_f32_dpp v66, v66, v66 row_bcast:31 row_mask:0xc bank_mask:0xf
	v_add_f32_dpp v67, v67, v67 row_bcast:31 row_mask:0xc bank_mask:0xf
	v_add_f32_dpp v68, v68, v68 row_shr:1 row_mask:0xf bank_mask:0xf
	v_add_f32_dpp v69, v69, v69 row_shr:1 row_mask:0xf bank_mask:0xf
	v_add_f32_dpp v70, v70, v70 row_shr:1 row_mask:0xf bank_mask:0xf
	v_add_f32_dpp v71, v71, v71 row_shr:1 row_mask:0xf bank_mask:0xf
	v_add_f32_dpp v68, v68, v68 row_shr:2 row_mask:0xf bank_mask:0xf
	v_add_f32_dpp v69, v69, v69 row_shr:2 row_mask:0xf bank_mask:0xf
	v_add_f32_dpp v70, v70, v70 row_shr:2 row_mask:0xf bank_mask:0xf
	v_add_f32_dpp v71, v71, v71 row_shr:2 row_mask:0xf bank_mask:0xf
	v_add_f32_dpp v68, v68, v68 row_shr:4 row_mask:0xf bank_mask:0xf
	v_add_f32_dpp v69, v69, v69 row_shr:4 row_mask:0xf bank_mask:0xf
	v_add_f32_dpp v70, v70, v70 row_shr:4 row_mask:0xf bank_mask:0xf
	v_add_f32_dpp v71, v71, v71 row_shr:4 row_mask:0xf bank_mask:0xf
	v_add_f32_dpp v68, v68, v68 row_shr:8 row_mask:0xf bank_mask:0xf
	v_add_f32_dpp v69, v69, v69 row_shr:8 row_mask:0xf bank_mask:0xf
	v_add_f32_dpp v70, v70, v70 row_shr:8 row_mask:0xf bank_mask:0xf
	v_add_f32_dpp v71, v71, v71 row_shr:8 row_mask:0xf bank_mask:0xf
; DI void scan_unit(const Params& p, int su) {
;     ...
; #pragma unroll
;         for (int i = 0; i < 65; ++i) s += (e0 + i < LSK) ? vals[i] : 0.f;
;         float incl = s;
; #pragma unroll
;         for (int o = 1; o < 64; o <<= 1) { const float t = __shfl_up(incl, o); if (lane >= o) incl += t; }
	v_add_f32_dpp v68, v68, v68 row_bcast:15 row_mask:0xa bank_mask:0xf
	v_add_f32_dpp v69, v69, v69 row_bcast:15 row_mask:0xa bank_mask:0xf
	v_add_f32_dpp v70, v70, v70 row_bcast:15 row_mask:0xa bank_mask:0xf
	v_add_f32_dpp v71, v71, v71 row_bcast:15 row_mask:0xa bank_mask:0xf
	v_add_f32_dpp v68, v68, v68 row_bcast:31 row_mask:0xc bank_mask:0xf
	v_add_f32_dpp v69, v69, v69 row_bcast:31 row_mask:0xc bank_mask:0xf
	v_add_f32_dpp v70, v70, v70 row_bcast:31 row_mask:0xc bank_mask:0xf
	v_add_f32_dpp v71, v71, v71 row_bcast:31 row_mask:0xc bank_mask:0xf
	v_add_f32_dpp v72, v72, v72 row_shr:1 row_mask:0xf bank_mask:0xf
	v_add_f32_dpp v73, v73, v73 row_shr:1 row_mask:0xf bank_mask:0xf
	v_add_f32_dpp v74, v74, v74 row_shr:1 row_mask:0xf bank_mask:0xf
	v_add_f32_dpp v75, v75, v75 row_shr:1 row_mask:0xf bank_mask:0xf
	v_add_f32_dpp v72, v72, v72 row_shr:2 row_mask:0xf bank_mask:0xf
	v_add_f32_dpp v73, v73, v73 row_shr:2 row_mask:0xf bank_mask:0xf
	v_add_f32_dpp v74, v74, v74 row_shr:2 row_mask:0xf bank_mask:0xf
	v_add_f32_dpp v75, v75, v75 row_shr:2 row_mask:0xf bank_mask:0xf
	v_add_f32_dpp v72, v72, v72 row_shr:4 row_mask:0xf bank_mask:0xf
	v_add_f32_dpp v73, v73, v73 row_shr:4 row_mask:0xf bank_mask:0xf
	v_add_f32_dpp v74, v74, v74 row_shr:4 row_mask:0xf bank_mask:0xf
	v_add_f32_dpp v75, v75, v75 row_shr:4 row_mask:0xf bank_mask:0xf
	v_add_f32_dpp v72, v72, v72 row_shr:8 row_mask:0xf bank_mask:0xf
	v_add_f32_dpp v73, v73, v73 row_shr:8 row_mask:0xf bank_mask:0xf
	v_add_f32_dpp v74, v74, v74 row_shr:8 row_mask:0xf bank_mask:0xf
	v_add_f32_dpp v75, v75, v75 row_shr:8 row_mask:0xf bank_mask:0xf
	v_add_f32_dpp v72, v72, v72 row_bcast:15 row_mask:0xa bank_mask:0xf
	v_add_f32_dpp v73, v73, v73 row_bcast:15 row_mask:0xa bank_mask:0xf
	v_add_f32_dpp v74, v74, v74 row_bcast:15 row_mask:0xa bank_mask:0xf
	v_add_f32_dpp v75, v75, v75 row_bcast:15 row_mask:0xa bank_mask:0xf
	v_add_f32_dpp v72, v72, v72 row_bcast:31 row_mask:0xc bank_mask:0xf
	v_add_f32_dpp v73, v73, v73 row_bcast:31 row_mask:0xc bank_mask:0xf
	v_add_f32_dpp v74, v74, v74 row_bcast:31 row_mask:0xc bank_mask:0xf
	v_add_f32_dpp v75, v75, v75 row_bcast:31 row_mask:0xc bank_mask:0xf
	v_add_f32_dpp v76, v76, v76 row_shr:1 row_mask:0xf bank_mask:0xf
	v_add_f32_dpp v77, v77, v77 row_shr:1 row_mask:0xf bank_mask:0xf
	v_add_f32_dpp v78, v78, v78 row_shr:1 row_mask:0xf bank_mask:0xf
	v_add_f32_dpp v79, v79, v79 row_shr:1 row_mask:0xf bank_mask:0xf
	v_add_f32_dpp v76, v76, v76 row_shr:2 row_mask:0xf bank_mask:0xf
	v_add_f32_dpp v77, v77, v77 row_shr:2 row_mask:0xf bank_mask:0xf
	v_add_f32_dpp v78, v78, v78 row_shr:2 row_mask:0xf bank_mask:0xf
	v_add_f32_dpp v79, v79, v79 row_shr:2 row_mask:0xf bank_mask:0xf
	v_add_f32_dpp v76, v76, v76 row_shr:4 row_mask:0xf bank_mask:0xf
	v_add_f32_dpp v77, v77, v77 row_shr:4 row_mask:0xf bank_mask:0xf
	v_add_f32_dpp v78, v78, v78 row_shr:4 row_mask:0xf bank_mask:0xf
	v_add_f32_dpp v79, v79, v79 row_shr:4 row_mask:0xf bank_mask:0xf
	v_add_f32_dpp v76, v76, v76 row_shr:8 row_mask:0xf bank_mask:0xf
	v_add_f32_dpp v77, v77, v77 row_shr:8 row_mask:0xf bank_mask:0xf
	v_add_f32_dpp v78, v78, v78 row_shr:8 row_mask:0xf bank_mask:0xf
	v_add_f32_dpp v79, v79, v79 row_shr:8 row_mask:0xf bank_mask:0xf
	v_add_f32_dpp v76, v76, v76 row_bcast:15 row_mask:0xa bank_mask:0xf
	v_add_f32_dpp v77, v77, v77 row_bcast:15 row_mask:0xa bank_mask:0xf
	v_add_f32_dpp v78, v78, v78 row_bcast:15 row_mask:0xa bank_mask:0xf
	v_add_f32_dpp v79, v79, v79 row_bcast:15 row_mask:0xa bank_mask:0xf
	v_add_f32_dpp v76, v76, v76 row_bcast:31 row_mask:0xc bank_mask:0xf
	v_add_f32_dpp v77, v77, v77 row_bcast:31 row_mask:0xc bank_mask:0xf
	v_add_f32_dpp v78, v78, v78 row_bcast:31 row_mask:0xc bank_mask:0xf
	v_add_f32_dpp v79, v79, v79 row_bcast:31 row_mask:0xc bank_mask:0xf
	v_add_f32_dpp v80, v80, v80 row_shr:1 row_mask:0xf bank_mask:0xf
	v_add_f32_dpp v81, v81, v81 row_shr:1 row_mask:0xf bank_mask:0xf
	v_add_f32_dpp v82, v82, v82 row_shr:1 row_mask:0xf bank_mask:0xf
	v_add_f32_dpp v83, v83, v83 row_shr:1 row_mask:0xf bank_mask:0xf
	v_add_f32_dpp v80, v80, v80 row_shr:2 row_mask:0xf bank_mask:0xf
	v_add_f32_dpp v81, v81, v81 row_shr:2 row_mask:0xf bank_mask:0xf
	v_add_f32_dpp v82, v82, v82 row_shr:2 row_mask:0xf bank_mask:0xf
	v_add_f32_dpp v83, v83, v83 row_shr:2 row_mask:0xf bank_mask:0xf
	v_add_f32_dpp v80, v80, v80 row_shr:4 row_mask:0xf bank_mask:0xf
	v_add_f32_dpp v81, v81, v81 row_shr:4 row_mask:0xf bank_mask:0xf
	v_add_f32_dpp v82, v82, v82 row_shr:4 row_mask:0xf bank_mask:0xf
	v_add_f32_dpp v83, v83, v83 row_shr:4 row_mask:0xf bank_mask:0xf
	v_add_f32_dpp v80, v80, v80 row_shr:8 row_mask:0xf bank_mask:0xf
	v_add_f32_dpp v81, v81, v81 row_shr:8 row_mask:0xf bank_mask:0xf
	v_add_f32_dpp v82, v82, v82 row_shr:8 row_mask:0xf bank_mask:0xf
	v_add_f32_dpp v83, v83, v83 row_shr:8 row_mask:0xf bank_mask:0xf
	v_add_f32_dpp v80, v80, v80 row_bcast:15 row_mask:0xa bank_mask:0xf
	v_add_f32_dpp v81, v81, v81 row_bcast:15 row_mask:0xa bank_mask:0xf
	v_add_f32_dpp v82, v82, v82 row_bcast:15 row_mask:0xa bank_mask:0xf
	v_add_f32_dpp v83, v83, v83 row_bcast:15 row_mask:0xa bank_mask:0xf
	v_add_f32_dpp v80, v80, v80 row_bcast:31 row_mask:0xc bank_mask:0xf
	v_add_f32_dpp v81, v81, v81 row_bcast:31 row_mask:0xc bank_mask:0xf
	v_add_f32_dpp v82, v82, v82 row_bcast:31 row_mask:0xc bank_mask:0xf
	v_add_f32_dpp v83, v83, v83 row_bcast:31 row_mask:0xc bank_mask:0xf
	v_add_f32_dpp v84, v84, v84 row_shr:1 row_mask:0xf bank_mask:0xf
	s_nop 0
	s_nop 0
	s_nop 0
	v_add_f32_dpp v84, v84, v84 row_shr:2 row_mask:0xf bank_mask:0xf
	s_nop 0
	s_nop 0
	s_nop 0
	v_add_f32_dpp v84, v84, v84 row_shr:4 row_mask:0xf bank_mask:0xf
	s_nop 0
; DI void scan_unit(const Params& p, int su) {
;     ...
;         float incl = s;
; #pragma unroll
;         for (int o = 1; o < 64; o <<= 1) { const float t = __shfl_up(incl, o); if (lane >= o) incl += t; }
;         float run = incl - s;
; #pragma unroll
;         for (int i = 0; i < 65; ++i) { const int e = e0 + i; if (e < LP) { run += vals[i]; dst[e] = run * LOG2E; } else dst[e] = 0.f; }
	s_nop 0
	s_nop 0
	v_add_f32_dpp v84, v84, v84 row_shr:8 row_mask:0xf bank_mask:0xf
	s_nop 0
	s_nop 0
	s_nop 0
	v_add_f32_dpp v84, v84, v84 row_bcast:15 row_mask:0xa bank_mask:0xf
	s_nop 0
	s_nop 0
	s_nop 0
	v_add_f32_dpp v84, v84, v84 row_bcast:31 row_mask:0xc bank_mask:0xf
	s_nop 0
	s_nop 0
	s_nop 0
	s_nop 1
	v_readlane_b32 s0, v20, 63
	s_nop 1
	v_add_f32_e32 v21, s0, v21
	s_nop 0
	v_readlane_b32 s0, v21, 63
	s_nop 1
	v_add_f32_e32 v22, s0, v22
	s_nop 0
	v_readlane_b32 s0, v22, 63
	s_nop 1
	v_add_f32_e32 v23, s0, v23
	s_nop 0
	v_readlane_b32 s0, v23, 63
	s_nop 1
	v_add_f32_e32 v24, s0, v24
	s_nop 0
	v_readlane_b32 s0, v24, 63
	s_nop 1
	v_add_f32_e32 v25, s0, v25
	s_nop 0
	v_readlane_b32 s0, v25, 63
	s_nop 1
	v_add_f32_e32 v26, s0, v26
	s_nop 0
	v_readlane_b32 s0, v26, 63
	s_nop 1
	v_add_f32_e32 v27, s0, v27
	s_nop 0
	v_readlane_b32 s0, v27, 63
	s_nop 1
	v_add_f32_e32 v28, s0, v28
	s_nop 0
	v_readlane_b32 s0, v28, 63
	s_nop 1
	v_add_f32_e32 v29, s0, v29
	s_nop 0
	v_readlane_b32 s0, v29, 63
	s_nop 1
	v_add_f32_e32 v30, s0, v30
	s_nop 0
	v_readlane_b32 s0, v30, 63
	s_nop 1
	v_add_f32_e32 v31, s0, v31
	s_nop 0
	v_readlane_b32 s0, v31, 63
	s_nop 1
	v_add_f32_e32 v32, s0, v32
	s_nop 0
	v_readlane_b32 s0, v32, 63
	s_nop 1
	v_add_f32_e32 v33, s0, v33
	s_nop 0
	v_readlane_b32 s0, v33, 63
	s_nop 1
	v_add_f32_e32 v34, s0, v34
	s_nop 0
	v_readlane_b32 s0, v34, 63
	s_nop 1
	v_add_f32_e32 v35, s0, v35
	s_nop 0
	v_readlane_b32 s0, v35, 63
	s_nop 1
	v_add_f32_e32 v36, s0, v36
	s_nop 0
	v_readlane_b32 s0, v36, 63
	s_nop 1
	v_add_f32_e32 v37, s0, v37
	s_nop 0
	v_readlane_b32 s0, v37, 63
	s_nop 1
	v_add_f32_e32 v38, s0, v38
	s_nop 0
	v_readlane_b32 s0, v38, 63
	s_nop 1
	v_add_f32_e32 v39, s0, v39
	s_nop 0
	v_readlane_b32 s0, v39, 63
	s_nop 1
	v_add_f32_e32 v40, s0, v40
	s_nop 0
	v_readlane_b32 s0, v40, 63
	s_nop 1
	v_add_f32_e32 v41, s0, v41
	s_nop 0
	v_readlane_b32 s0, v41, 63
	s_nop 1
	v_add_f32_e32 v42, s0, v42
	s_nop 0
	v_readlane_b32 s0, v42, 63
	s_nop 1
	v_add_f32_e32 v43, s0, v43
	s_nop 0
	v_readlane_b32 s0, v43, 63
	s_nop 1
	v_add_f32_e32 v44, s0, v44
	s_nop 0
	v_readlane_b32 s0, v44, 63
	s_nop 1
	v_add_f32_e32 v45, s0, v45
	s_nop 0
	v_readlane_b32 s0, v45, 63
	s_nop 1
	v_add_f32_e32 v46, s0, v46
	s_nop 0
	v_readlane_b32 s0, v46, 63
	s_nop 1
	v_add_f32_e32 v47, s0, v47
	s_nop 0
	v_readlane_b32 s0, v47, 63
	s_nop 1
	v_add_f32_e32 v48, s0, v48
	s_nop 0
	v_readlane_b32 s0, v48, 63
	s_nop 1
	v_add_f32_e32 v49, s0, v49
	s_nop 0
	v_readlane_b32 s0, v49, 63
	s_nop 1
	v_add_f32_e32 v50, s0, v50
	s_nop 0
	v_readlane_b32 s0, v50, 63
	s_nop 1
	v_add_f32_e32 v51, s0, v51
	s_nop 0
	v_readlane_b32 s0, v51, 63
	s_nop 1
	v_add_f32_e32 v52, s0, v52
	s_nop 0
	v_readlane_b32 s0, v52, 63
	s_nop 1
	v_add_f32_e32 v53, s0, v53
	s_nop 0
	v_readlane_b32 s0, v53, 63
	s_nop 1
	v_add_f32_e32 v54, s0, v54
	s_nop 0
	v_readlane_b32 s0, v54, 63
	s_nop 1
	v_add_f32_e32 v55, s0, v55
	s_nop 0
	v_readlane_b32 s0, v55, 63
	s_nop 1
	v_add_f32_e32 v56, s0, v56
	s_nop 0
	v_readlane_b32 s0, v56, 63
	s_nop 1
	v_add_f32_e32 v57, s0, v57
	s_nop 0
	v_readlane_b32 s0, v57, 63
	s_nop 1
	v_add_f32_e32 v58, s0, v58
	s_nop 0
	v_readlane_b32 s0, v58, 63
	s_nop 1
	v_add_f32_e32 v59, s0, v59
	s_nop 0
	v_readlane_b32 s0, v59, 63
	s_nop 1
	v_add_f32_e32 v60, s0, v60
	s_nop 0
	v_readlane_b32 s0, v60, 63
	s_nop 1
	v_add_f32_e32 v61, s0, v61
	s_nop 0
	v_readlane_b32 s0, v61, 63
	s_nop 1
	v_add_f32_e32 v62, s0, v62
	s_nop 0
	v_readlane_b32 s0, v62, 63
	s_nop 1
	v_add_f32_e32 v63, s0, v63
	s_nop 0
	v_readlane_b32 s0, v63, 63
	s_nop 1
	v_add_f32_e32 v64, s0, v64
	s_nop 0
	v_readlane_b32 s0, v64, 63
	s_nop 1
	v_add_f32_e32 v65, s0, v65
	s_nop 0
	v_readlane_b32 s0, v65, 63
	s_nop 1
	v_add_f32_e32 v66, s0, v66
	s_nop 0
	v_readlane_b32 s0, v66, 63
	s_nop 1
	v_add_f32_e32 v67, s0, v67
	s_nop 0
	v_readlane_b32 s0, v67, 63
	s_nop 1
	v_add_f32_e32 v68, s0, v68
	s_nop 0
	v_readlane_b32 s0, v68, 63
	s_nop 1
	v_add_f32_e32 v69, s0, v69
	s_nop 0
	v_readlane_b32 s0, v69, 63
	s_nop 1
	v_add_f32_e32 v70, s0, v70
	s_nop 0
	v_readlane_b32 s0, v70, 63
	s_nop 1
	v_add_f32_e32 v71, s0, v71
	s_nop 0
	v_readlane_b32 s0, v71, 63
	s_nop 1
	v_add_f32_e32 v72, s0, v72
	s_nop 0
	v_readlane_b32 s0, v72, 63
	s_nop 1
	v_add_f32_e32 v73, s0, v73
	s_nop 0
	v_readlane_b32 s0, v73, 63
	s_nop 1
	v_add_f32_e32 v74, s0, v74
	s_nop 0
	v_readlane_b32 s0, v74, 63
	s_nop 1
	v_add_f32_e32 v75, s0, v75
	s_nop 0
	v_readlane_b32 s0, v75, 63
	s_nop 1
	v_add_f32_e32 v76, s0, v76
	s_nop 0
	v_readlane_b32 s0, v76, 63
	s_nop 1
	v_add_f32_e32 v77, s0, v77
	s_nop 0
	v_readlane_b32 s0, v77, 63
	s_nop 1
	v_add_f32_e32 v78, s0, v78
	s_nop 0
	v_readlane_b32 s0, v78, 63
	s_nop 1
	v_add_f32_e32 v79, s0, v79
	s_nop 0
	v_readlane_b32 s0, v79, 63
	s_nop 1
	v_add_f32_e32 v80, s0, v80
	s_nop 0
	v_readlane_b32 s0, v80, 63
	s_nop 1
	v_add_f32_e32 v81, s0, v81
	s_nop 0
	v_readlane_b32 s0, v81, 63
	s_nop 1
	v_add_f32_e32 v82, s0, v82
	s_nop 0
	v_readlane_b32 s0, v82, 63
	s_nop 1
	v_add_f32_e32 v83, s0, v83
	s_nop 0
	v_readlane_b32 s0, v83, 63
	s_nop 1
	v_add_f32_e32 v84, s0, v84
	v_mul_f32_e32 v20, 0x3fb8aa3b, v20
	v_mul_f32_e32 v21, 0x3fb8aa3b, v21
	v_mul_f32_e32 v22, 0x3fb8aa3b, v22
	v_mul_f32_e32 v23, 0x3fb8aa3b, v23
	v_mul_f32_e32 v24, 0x3fb8aa3b, v24
	v_mul_f32_e32 v25, 0x3fb8aa3b, v25
	v_mul_f32_e32 v26, 0x3fb8aa3b, v26
	v_mul_f32_e32 v27, 0x3fb8aa3b, v27
	v_mul_f32_e32 v28, 0x3fb8aa3b, v28
	v_mul_f32_e32 v29, 0x3fb8aa3b, v29
	v_mul_f32_e32 v30, 0x3fb8aa3b, v30
	v_mul_f32_e32 v31, 0x3fb8aa3b, v31
	v_mul_f32_e32 v32, 0x3fb8aa3b, v32
	v_mul_f32_e32 v33, 0x3fb8aa3b, v33
	v_mul_f32_e32 v34, 0x3fb8aa3b, v34
	v_mul_f32_e32 v35, 0x3fb8aa3b, v35
	v_mul_f32_e32 v36, 0x3fb8aa3b, v36
;     __host__ __device__ bool next(int i, Unit& u) const {
;         const long L = (long)i * G + c; if (L >= nwg) return false;
;         int wgid = (int)L; { const int q = nwg / NXCD, r = nwg % NXCD, xcd = wgid % NXCD, off = wgid / NXCD; wgid = (xcd < r ? xcd * (q + 1) : r * (q + 1) + (xcd - r) * q) + off; }
;         const int nig = WGM * nN, gid = wgid / nig, fm = gid * WGM, gsz = (nM - fm) < WGM ? (nM - fm) : WGM;
;         u.pm = fm + ((wgid % nig) % gsz); u.pn = (wgid % nig) / gsz; return true;
; DI void scan_unit(const Params& p, int su) {
;     ...
;         float run = incl - s;
; #pragma unroll
;         for (int i = 0; i < 65; ++i) { const int e = e0 + i; if (e < LP) { run += vals[i]; dst[e] = run * LOG2E; } else dst[e] = 0.f; }
	v_mul_f32_e32 v37, 0x3fb8aa3b, v37
	v_mul_f32_e32 v38, 0x3fb8aa3b, v38
	v_mul_f32_e32 v39, 0x3fb8aa3b, v39
	v_mul_f32_e32 v40, 0x3fb8aa3b, v40
	v_mul_f32_e32 v41, 0x3fb8aa3b, v41
	v_mul_f32_e32 v42, 0x3fb8aa3b, v42
	v_mul_f32_e32 v43, 0x3fb8aa3b, v43
	v_mul_f32_e32 v44, 0x3fb8aa3b, v44
	v_mul_f32_e32 v45, 0x3fb8aa3b, v45
	v_mul_f32_e32 v46, 0x3fb8aa3b, v46
	v_mul_f32_e32 v47, 0x3fb8aa3b, v47
	v_mul_f32_e32 v48, 0x3fb8aa3b, v48
	v_mul_f32_e32 v49, 0x3fb8aa3b, v49
	v_mul_f32_e32 v50, 0x3fb8aa3b, v50
	v_mul_f32_e32 v51, 0x3fb8aa3b, v51
	v_mul_f32_e32 v52, 0x3fb8aa3b, v52
	v_mul_f32_e32 v53, 0x3fb8aa3b, v53
	v_mul_f32_e32 v54, 0x3fb8aa3b, v54
	v_mul_f32_e32 v55, 0x3fb8aa3b, v55
	v_mul_f32_e32 v56, 0x3fb8aa3b, v56
	v_mul_f32_e32 v57, 0x3fb8aa3b, v57
	v_mul_f32_e32 v58, 0x3fb8aa3b, v58
	v_mul_f32_e32 v59, 0x3fb8aa3b, v59
	v_mul_f32_e32 v60, 0x3fb8aa3b, v60
	v_mul_f32_e32 v61, 0x3fb8aa3b, v61
	v_mul_f32_e32 v62, 0x3fb8aa3b, v62
	v_mul_f32_e32 v63, 0x3fb8aa3b, v63
	v_mul_f32_e32 v64, 0x3fb8aa3b, v64
	v_mul_f32_e32 v65, 0x3fb8aa3b, v65
	v_mul_f32_e32 v66, 0x3fb8aa3b, v66
	v_mul_f32_e32 v67, 0x3fb8aa3b, v67
	v_mul_f32_e32 v68, 0x3fb8aa3b, v68
	v_mul_f32_e32 v69, 0x3fb8aa3b, v69
	v_mul_f32_e32 v70, 0x3fb8aa3b, v70
	v_mul_f32_e32 v71, 0x3fb8aa3b, v71
	v_mul_f32_e32 v72, 0x3fb8aa3b, v72
	v_mul_f32_e32 v73, 0x3fb8aa3b, v73
	v_mul_f32_e32 v74, 0x3fb8aa3b, v74
	v_mul_f32_e32 v75, 0x3fb8aa3b, v75
	v_mul_f32_e32 v76, 0x3fb8aa3b, v76
	v_mul_f32_e32 v77, 0x3fb8aa3b, v77
	v_mul_f32_e32 v78, 0x3fb8aa3b, v78
	v_mul_f32_e32 v79, 0x3fb8aa3b, v79
	v_mul_f32_e32 v80, 0x3fb8aa3b, v80
	v_mul_f32_e32 v81, 0x3fb8aa3b, v81
	v_mul_f32_e32 v82, 0x3fb8aa3b, v82
	v_mul_f32_e32 v83, 0x3fb8aa3b, v83
	v_mul_f32_e32 v84, 0x3fb8aa3b, v84
	global_store_dword v13, v20, s[6:7]
	global_store_dword v13, v21, s[6:7] offset:256
	global_store_dword v13, v22, s[6:7] offset:512
	global_store_dword v13, v23, s[6:7] offset:768
	global_store_dword v13, v24, s[6:7] offset:1024
	global_store_dword v13, v25, s[6:7] offset:1280
	global_store_dword v13, v26, s[6:7] offset:1536
	global_store_dword v13, v27, s[6:7] offset:1792
	global_store_dword v13, v28, s[6:7] offset:2048
	global_store_dword v13, v29, s[6:7] offset:2304
	global_store_dword v13, v30, s[6:7] offset:2560
	global_store_dword v13, v31, s[6:7] offset:2816
	global_store_dword v13, v32, s[6:7] offset:3072
	global_store_dword v13, v33, s[6:7] offset:3328
	global_store_dword v13, v34, s[6:7] offset:3584
	global_store_dword v13, v35, s[6:7] offset:3840
	s_add_u32 s6, s6, 0x1000
	s_addc_u32 s7, s7, 0
	global_store_dword v13, v36, s[6:7]
	global_store_dword v13, v37, s[6:7] offset:256
	global_store_dword v13, v38, s[6:7] offset:512
	global_store_dword v13, v39, s[6:7] offset:768
	global_store_dword v13, v40, s[6:7] offset:1024
	global_store_dword v13, v41, s[6:7] offset:1280
	global_store_dword v13, v42, s[6:7] offset:1536
	global_store_dword v13, v43, s[6:7] offset:1792
	global_store_dword v13, v44, s[6:7] offset:2048
	global_store_dword v13, v45, s[6:7] offset:2304
	global_store_dword v13, v46, s[6:7] offset:2560
	global_store_dword v13, v47, s[6:7] offset:2816
	global_store_dword v13, v48, s[6:7] offset:3072
	global_store_dword v13, v49, s[6:7] offset:3328
	global_store_dword v13, v50, s[6:7] offset:3584
	global_store_dword v13, v51, s[6:7] offset:3840
	s_add_u32 s6, s6, 0x1000
	s_addc_u32 s7, s7, 0
	global_store_dword v13, v52, s[6:7]
	global_store_dword v13, v53, s[6:7] offset:256
	global_store_dword v13, v54, s[6:7] offset:512
	global_store_dword v13, v55, s[6:7] offset:768
	global_store_dword v13, v56, s[6:7] offset:1024
	global_store_dword v13, v57, s[6:7] offset:1280
	global_store_dword v13, v58, s[6:7] offset:1536
	global_store_dword v13, v59, s[6:7] offset:1792
	global_store_dword v13, v60, s[6:7] offset:2048
	global_store_dword v13, v61, s[6:7] offset:2304
	global_store_dword v13, v62, s[6:7] offset:2560
	global_store_dword v13, v63, s[6:7] offset:2816
	global_store_dword v13, v64, s[6:7] offset:3072
	global_store_dword v13, v65, s[6:7] offset:3328
	global_store_dword v13, v66, s[6:7] offset:3584
	global_store_dword v13, v67, s[6:7] offset:3840
	s_add_u32 s6, s6, 0x1000
	s_addc_u32 s7, s7, 0
	global_store_dword v13, v68, s[6:7]
	global_store_dword v13, v69, s[6:7] offset:256
	global_store_dword v13, v70, s[6:7] offset:512
	global_store_dword v13, v71, s[6:7] offset:768
	global_store_dword v13, v72, s[6:7] offset:1024
	global_store_dword v13, v73, s[6:7] offset:1280
	global_store_dword v13, v74, s[6:7] offset:1536
	global_store_dword v13, v75, s[6:7] offset:1792
	global_store_dword v13, v76, s[6:7] offset:2048
	global_store_dword v13, v77, s[6:7] offset:2304
	global_store_dword v13, v78, s[6:7] offset:2560
	global_store_dword v13, v79, s[6:7] offset:2816
	global_store_dword v13, v80, s[6:7] offset:3072
	global_store_dword v13, v81, s[6:7] offset:3328
	global_store_dword v13, v82, s[6:7] offset:3584
	global_store_dword v13, v83, s[6:7] offset:3840
	s_add_u32 s6, s6, 0x1000
	s_addc_u32 s7, s7, 0
	s_mov_b64 exec, s[4:5]
	global_store_dword v13, v84, s[6:7]
	s_mov_b64 exec, -1
	s_branch .Lscn_done
.Lscn_done:
.LBB0_127:
	s_cmpk_lt_i32 s2, 0x430
	s_cselect_b64 s[4:5], -1, 0
	s_cmpk_gt_i32 s2, 0x42f
	v_readfirstlane_b32 s14, v138
	s_barrier
	s_cbranch_scc1 .LBB0_129
	s_ashr_i32 s0, s2, 31
	s_lshr_b32 s0, s0, 29
	s_add_i32 s0, s2, s0
	s_ashr_i32 s1, s0, 3
	s_and_b32 s0, s0, -8
	s_sub_i32 s0, s2, s0
	s_cmp_lt_i32 s0, 0
	s_movk_i32 s6, 0x87
	s_cselect_b32 s6, s6, 0x86
	s_mul_i32 s0, s0, s6
	s_add_i32 s0, s0, s1
	s_ashr_i32 s1, s0, 31
	s_lshr_b32 s1, s1, 25
	s_add_i32 s1, s0, s1
	s_ashr_i32 s1, s1, 7
	s_lshl_b32 s6, s1, 3
	s_sub_i32 s7, 0x43, s6
	s_lshl_b32 s1, s1, 7
	s_min_u32 s7, s7, 8
	s_sub_i32 s8, s0, s1
	s_sext_i32_i8 s0, s8
	v_cvt_f32_ubyte0_e32 v2, s7
	v_cvt_f32_i32_e32 v1, s0
	v_rcp_iflag_f32_e32 v3, v2
	s_ashr_i32 s0, s0, 30
	s_or_b32 s9, s0, 1
	v_mul_f32_e32 v3, v1, v3
	v_trunc_f32_e32 v3, v3
	v_fma_f32 v1, -v3, v2, v1
	v_cvt_i32_f32_e32 v3, v3
	v_cmp_ge_f32_e64 s[0:1], |v1|, v2
	s_and_b64 s[0:1], s[0:1], exec
	s_cselect_b32 s0, s9, 0
	v_readfirstlane_b32 s1, v3
	s_add_i32 s1, s1, s0
	s_sext_i32_i8 s0, s1
	s_mul_i32 s1, s1, s7
	s_sub_i32 s1, s8, s1
	s_sext_i32_i8 s1, s1
	s_add_i32 s6, s6, s1
